# v36
# speedup vs baseline: 1.0138x; 1.0012x over previous
; DI void dsa_item(const Params& p, int b, int blk) {
;     ...
;   constexpr int PSTR = 264;
;   u16* Pb = (u16*)(smem + w * 8192);
;   char* Vc = smem + (w < 4 ? DS_CAND + w * 8192 : DS_MASK + (w - 4) * 8192);
;   const int g16 = lane >> 4, n16 = lane & 15;
;   for (int i = lane; i < PSTR; i += 64) Pb[8 * PSTR + i] = 0;
;   unsigned taddr[8][2];
;   {
;     const unsigned q = n16 >> 2, pp = lane & 3;
;     #pragma unroll
;     for (int c = 0; c < 8; ++c)
;       #pragma unroll
;       for (int t = 0; t < 2; ++t) {
;         const unsigned row = 8 * g16 + 4 * t + q, ch = 2 * c + (pp >> 1);
;         taddr[c][t] = (unsigned)(size_t)(Vc - smem) + 256u * row + 16u * (ch ^ (((row & 3) << 2) | ((row >> 2) & 3))) + 8u * (pp & 1);
;       }
;   }
;   const unsigned lds_base = (unsigned)(size_t)(__attribute__((address_space(3))) char*)smem;
;   const int arow = n16 < 8 ? n16 : 8;
.LBB0_1664:
	s_or_b64 exec, exec, s[4:5]
	v_lshrrev_b32_e32 v7, 4, v187
	v_cmp_gt_i32_e32 vcc, 4, v188
	v_mov_b32_e32 v0, 0x14c00
	v_mov_b32_e32 v2, 0x14000
	v_lshlrev_b32_e32 v156, 3, v7
	v_lshlrev_b32_e32 v12, 1, v7
	v_cndmask_b32_e32 v6, v0, v2, vcc
	v_bfe_u32 v0, v189, 2, 2
	v_and_b32_e32 v9, 12, v189
	v_and_b32_e32 v13, 2, v12
	v_or_b32_e32 v157, 4, v156
	v_bfe_u32 v3, v189, 1, 1
	v_or_b32_e32 v11, v156, v0
	v_or_b32_e32 v14, v13, v9
	v_or_b32_e32 v15, v157, v0
	v_bfe_u32 v0, v157, 2, 2
	v_and_b32_e32 v2, 3, v189
	v_or_b32_e32 v14, v14, v3
	v_bitop3_b32 v17, v0, v3, v9 bitop3:0x36
	v_or_b32_e32 v18, 2, v3
	v_or_b32_e32 v20, 4, v3
	v_or_b32_e32 v22, 6, v3
	v_or_b32_e32 v24, 8, v3
	v_or_b32_e32 v26, 10, v3
	v_or_b32_e32 v28, 12, v3
	v_or_b32_e32 v3, 14, v3
	v_and_b32_e32 v8, 15, v189
	v_bitop3_b32 v19, v13, v18, v9 bitop3:0x36
	v_bitop3_b32 v18, v0, v18, v9 bitop3:0x36
	v_bitop3_b32 v21, v13, v20, v9 bitop3:0x36
	v_bitop3_b32 v20, v0, v20, v9 bitop3:0x36
	v_bitop3_b32 v23, v13, v22, v9 bitop3:0x36
	v_bitop3_b32 v22, v0, v22, v9 bitop3:0x36
	v_bitop3_b32 v25, v13, v24, v9 bitop3:0x36
	v_bitop3_b32 v24, v0, v24, v9 bitop3:0x36
	v_bitop3_b32 v27, v13, v26, v9 bitop3:0x36
	v_bitop3_b32 v26, v0, v26, v9 bitop3:0x36
	v_bitop3_b32 v29, v13, v28, v9 bitop3:0x36
	v_bitop3_b32 v28, v0, v28, v9 bitop3:0x36
	v_bitop3_b32 v30, v13, v3, v9 bitop3:0x36
	v_bitop3_b32 v9, v0, v3, v9 bitop3:0x36
	v_lshlrev_b32_e32 v0, 7, v2
	v_min_u32_e32 v32, 8, v8
	v_lshl_add_u64 v[2:3], s[14:15], 0, v[0:1]
	s_mov_b64 s[4:5], 0xa0cda00
	v_lshlrev_b32_e32 v0, 4, v8
	v_add_u32_e32 v5, 0, v4
	v_lshlrev_b32_e32 v10, 3, v189
	s_waitcnt vmcnt(0)
	v_lshl_add_u64 v[146:147], v[2:3], 0, s[4:5]
	v_lshl_add_u64 v[2:3], s[14:15], 0, v[0:1]
	v_mul_u32_u24_e32 v0, 0x210, v32
	v_and_b32_e32 v32, 48, v187
	v_add3_u32 v161, v5, v0, v32
	v_and_or_b32 v0, v10, 8, 0
	s_mov_b64 s[4:5], 0x15bada00
	v_add3_u32 v0, v6, v4, v0
	v_lshl_add_u64 v[148:149], v[2:3], 0, s[4:5]
	v_lshl_add_u32 v2, v11, 8, v0
	v_lshl_add_u32 v0, v15, 8, v0
	v_lshl_add_u32 v163, v17, 4, v0
	v_lshl_add_u32 v165, v18, 4, v0
	v_lshl_add_u32 v167, v20, 4, v0
	v_lshl_add_u32 v169, v22, 4, v0
	v_lshl_add_u32 v171, v24, 4, v0
	v_lshl_add_u32 v173, v26, 4, v0
	v_lshl_add_u32 v175, v28, 4, v0
	v_lshl_add_u32 v177, v9, 4, v0
	v_lshlrev_b32_e32 v0, 1, v8
	v_lshlrev_b32_e32 v33, 1, v187
	v_lshl_add_u32 v162, v14, 4, v2
	v_lshl_add_u32 v164, v19, 4, v2
	v_lshl_add_u32 v166, v21, 4, v2
	v_lshl_add_u32 v168, v23, 4, v2
	v_lshl_add_u32 v170, v25, 4, v2
	v_lshl_add_u32 v172, v27, 4, v2
	v_lshl_add_u32 v174, v29, 4, v2
	v_lshl_add_u32 v176, v30, 4, v2
	v_lshl_add_u64 v[2:3], s[14:15], 0, v[0:1]
	v_bitop3_b32 v0, v12, v8, 2 bitop3:0x6c
	v_add_u32_e32 v31, v5, v6
	v_add_u32_e32 v160, v5, v33
	v_lshlrev_b32_e32 v5, 4, v0
	v_bitop3_b32 v0, v12, v8, 4 bitop3:0x36
	v_lshlrev_b32_e32 v9, 4, v0
	v_bitop3_b32 v0, v13, v8, 8 bitop3:0x36
	v_lshrrev_b32_e32 v16, 2, v157
	v_lshlrev_b32_e32 v11, 4, v0
	v_bitop3_b32 v0, v12, v8, 12 bitop3:0x36
	v_or_b32_e32 v195, 5, v156
	v_lshlrev_b32_e32 v12, 4, v0
	v_bitop3_b32 v0, v16, v8, 3 bitop3:0x6c
	v_lshlrev_b32_e32 v15, 4, v0
	v_lshrrev_b32_e32 v0, 2, v195
	v_or_b32_e32 v196, 6, v156
	v_bitop3_b32 v0, v0, v8, 4 bitop3:0x36
	v_lshlrev_b32_e32 v17, 4, v0
	v_bfe_u32 v0, v196, 2, 2
	v_or_b32_e32 v197, 7, v156
	v_bitop3_b32 v0, v0, v8, 8 bitop3:0x36
	v_lshlrev_b32_e32 v19, 4, v0
	v_lshrrev_b32_e32 v0, 2, v197
	v_bitop3_b32 v0, v0, v8, 12 bitop3:0x36
	v_lshlrev_b32_e32 v8, 4, v0
	v_lshlrev_b32_e32 v0, 9, v7
	v_or_b32_e32 v192, 1, v156
	v_or_b32_e32 v193, 2, v156
	v_or_b32_e32 v194, 3, v156
	v_lshl_add_u64 v[2:3], v[2:3], 0, v[0:1]
	s_mov_b64 s[4:5], 0x18349a00
	s_add_u32 s0, s14, 0x1538da00
	v_lshl_add_u32 v4, v7, 11, v31
	v_lshl_add_u32 v6, v192, 8, v31
	v_lshl_add_u32 v10, v193, 8, v31
	v_lshl_add_u32 v13, v194, 8, v31
	v_lshl_add_u32 v14, v157, 8, v31
	v_lshl_add_u32 v16, v195, 8, v31
	v_lshl_add_u32 v18, v196, 8, v31
	v_lshl_add_u32 v20, v197, 8, v31
	v_lshl_add_u64 v[150:151], v[2:3], 0, s[4:5]
	v_lshl_or_b32 v0, v188, 11, v32
	v_readlane_b32 s4, v255, 7
	s_addc_u32 s1, s15, 0
	v_lshlrev_b32_e32 v158, 2, v188
	v_add_u32_e32 v159, s3, v33
	v_cmp_gt_u32_e64 s[6:7], 32, v187
	v_cmp_gt_u32_e64 s[8:9], 16, v187
	v_or_b32_e32 v189, 64, v187
	v_or_b32_e32 v190, 0x80, v187
	v_or_b32_e32 v191, 0xc0, v187
	v_add_u32_e32 v188, s4, v0
	s_mov_b32 s24, 0
	v_add_u32_e32 v198, v4, v5
	v_add_u32_e32 v199, v6, v9
	v_add_u32_e32 v200, v10, v11
	v_add_u32_e32 v201, v13, v12
	v_add_u32_e32 v202, v14, v15
	v_add_u32_e32 v203, v16, v17
	v_add_u32_e32 v204, v18, v19
	v_add_u32_e32 v205, v20, v8
	v_readfirstlane_b32 s12, v148
	v_readfirstlane_b32 s13, v149
	s_lshl_b64 s[14:15], s[16:17], 8
	s_nop 0
	s_add_u32 s12, s12, s14
	s_addc_u32 s13, s13, s15
	s_add_u32 s14, s0, s14
	s_addc_u32 s15, s1, s15
	v_readfirstlane_b32 s100, v178
	s_nop 3
	s_lshr_b32 s100, s100, 6

; DI void dsa_item(const Params& p, int b, int blk) {
;     ...
;     const int qq = w * 4 + qq4;
;     const int t = q0 + qq;
;     if (t >= LVALID) continue;
;     const size_t row = rowbase + t;
;     const int cnt = min((int)selcnt[qq], TOPK);
;     const u16* qptr = Aq + row * 512 + (lane & 3) * 64;
;     bf16x8 qa[8], qb[8];
;     #pragma unroll
;     for (int c = 0; c < 8; ++c) { qa[c] = ldg<bf16x8>(qptr + c * 8); qb[c] = ldg<bf16x8>(qptr + 256 + c * 8); }
;     float sc[4][8];
;     bf16x8 ka[2][8], kb[2][8];
;     bool valid[4];
;     {
;       const int ks = lane;
;       valid[0] = ks < cnt;
;       const int idx = valid[0] ? (int)sel[qq * 256 + ks] : 0;
;       const u16* kptr = Ak + (rowbase + idx) * 128;
;       #pragma unroll
;       for (int c = 0; c < 8; ++c) { ka[0][c] = ldg<bf16x8>(kptr + c * 8); kb[0][c] = ldg<bf16x8>(kptr + 64 + c * 8); }
;     }
;     #pragma unroll
;     for (int rd = 0; rd < 4; ++rd) {
;       if (rd < 3) {
;         const int ks = (rd + 1) * 64 + lane;
;         valid[rd + 1] = ks < cnt;
;         const int idx = valid[rd + 1] ? (int)sel[qq * 256 + ks] : 0;
;         const u16* kptr = Ak + (rowbase + idx) * 128;
;         #pragma unroll
;         for (int c = 0; c < 8; ++c) { ka[(rd + 1) & 1][c] = ldg<bf16x8>(kptr + c * 8); kb[(rd + 1) & 1][c] = ldg<bf16x8>(kptr + 64 + c * 8); }
;     ...
;     {
;       const u32x4 si = *(const u32x4*)(sel + qq * 256 + 8 * g16);
;       #pragma unroll
;       for (int j = 0; j < 8; ++j) {
;         const int ks = 8 * g16 + j;
;         const int idx = ks < cnt ? (int)((si[j >> 1] >> (16 * (j & 1))) & 0xffffu) : 0;
;         vr[j] = ldg<u32x4>(Av + (rowbase + idx) * 128 + n16 * 8);
;       }
;     }
.LBB0_1667:
	v_add_u32_e32 v66, s24, v158
	s_waitcnt vmcnt(0)
	v_add_u32_e32 v2, s36, v66
	s_movk_i32 s4, 0x2010
	v_cmp_gt_i32_e32 vcc, s4, v2
	s_and_saveexec_b64 s[4:5], vcc
	s_cbranch_execz .LBB0_1666
	v_ashrrev_i32_e32 v3, 31, v2
	v_lshl_add_u32 v0, v66, 2, 0
	v_add_u32_e32 v0, 0x1ca80, v0
	ds_read_b32 v0, v0
	v_and_b32_e32 v130, 15, v187
	v_lshlrev_b32_e32 v133, 9, v66
	v_lshl_add_u32 v133, v130, 1, v133
	v_add_u32_e32 v133, 0x10000, v133
	ds_read_u16 v18, v133
	ds_read_u16 v22, v133 offset:32
	ds_read_u16 v26, v133 offset:64
	ds_read_u16 v30, v133 offset:96
	ds_read_u16 v34, v133 offset:128
	ds_read_u16 v38, v133 offset:160
	ds_read_u16 v42, v133 offset:192
	ds_read_u16 v46, v133 offset:224
	ds_read_u16 v50, v133 offset:256
	ds_read_u16 v54, v133 offset:288
	ds_read_u16 v58, v133 offset:320
	ds_read_u16 v62, v133 offset:352
	ds_read_u16 v66, v133 offset:384
	ds_read_u16 v70, v133 offset:416
	ds_read_u16 v74, v133 offset:448
	ds_read_u16 v78, v133 offset:480
	v_lshl_add_u64 v[152:153], s[16:17], 0, v[2:3]
	v_and_b32_e32 v142, 12, v187
	v_lshlrev_b32_e32 v142, 7, v142
	v_and_b32_e32 v144, 48, v187
	v_or_b32_e32 v142, v142, v144
	v_mov_b32_e32 v143, 0
	v_mov_b32_e32 v145, 0
	v_mov_b32_e32 v134, v144
	v_lshlrev_b64 v[4:5], 10, v[152:153]
	v_lshl_add_u64 v[4:5], v[146:147], 0, v[4:5]
	v_lshl_add_u64 v[142:143], v[4:5], 0, v[142:143]
	v_xor_b32_e32 v136, 16, v187
	v_lshlrev_b32_e32 v136, 2, v136
	v_xor_b32_e32 v137, 32, v187
	v_lshlrev_b32_e32 v137, 2, v137
	v_lshrrev_b32_e32 v138, 6, v178
	v_lshlrev_b32_e32 v138, 13, v138
	v_mul_u32_u24_e32 v252, 0x210, v130
	v_add3_u32 v138, v138, v252, v156
	v_mov_b32_e32 v139, 0xf149f2ca
	v_mov_b32_e32 v141, 0
	v_mov_b32_e32 v2, 0
	v_mov_b32_e32 v3, 0
	v_mov_b32_e32 v4, 0
	v_mov_b32_e32 v5, 0
	v_mov_b32_e32 v6, 0
	v_mov_b32_e32 v7, 0
	v_mov_b32_e32 v8, 0
	v_mov_b32_e32 v9, 0
	v_mov_b32_e32 v10, 0
	v_mov_b32_e32 v11, 0
	v_mov_b32_e32 v12, 0
	v_mov_b32_e32 v13, 0
	v_mov_b32_e32 v14, 0
	v_mov_b32_e32 v15, 0
	v_mov_b32_e32 v16, 0
	v_mov_b32_e32 v17, 0
	s_mov_b32 exec_lo, 0x000f000f
	s_mov_b32 exec_hi, 0x000f000f
	global_load_dwordx4 v[2:5], v[142:143], off
	global_load_dwordx4 v[6:9], v[142:143], off offset:64
	s_mov_b32 exec_lo, 0x00f000f0
	s_mov_b32 exec_hi, 0x00f000f0
	global_load_dwordx4 v[10:13], v[142:143], off
	global_load_dwordx4 v[14:17], v[142:143], off offset:64
	s_mov_b64 exec, -1
	s_waitcnt lgkmcnt(0)
	v_min_i32_e32 v206, 0x100, v0
	v_sub_u32_e32 v131, v206, v130
	v_lshrrev_b32_e32 v132, 1, v156
	v_sub_u32_e32 v132, v206, v132
	v_readfirstlane_b32 s100, v206
	v_add_u32_e32 v242, 0xffffffc0, v188
	v_mov_b32_e32 v241, 0
	v_lshlrev_b32_e32 v253, 4, v130
	ds_read_b128 v[248:251], v242
	s_waitcnt lgkmcnt(0)
	v_cmp_lt_i32_e32 vcc, v156, v206
	s_nop 1
	v_cndmask_b32_sdwa v240, v1, v248, vcc dst_sel:DWORD dst_unused:UNUSED_PAD src0_sel:DWORD src1_sel:WORD_0
	v_cmp_lt_i32_e32 vcc, v192, v206
	v_lshl_add_u32 v244, v240, 8, v253
	global_load_dwordx4 v[208:211], v244, s[12:13]
	v_cndmask_b32_sdwa v240, v1, v248, vcc dst_sel:DWORD dst_unused:UNUSED_PAD src0_sel:DWORD src1_sel:WORD_1
	v_cmp_lt_i32_e32 vcc, v193, v206
	v_lshl_add_u32 v245, v240, 8, v253
	global_load_dwordx4 v[212:215], v245, s[12:13]
	v_cndmask_b32_sdwa v240, v1, v249, vcc dst_sel:DWORD dst_unused:UNUSED_PAD src0_sel:DWORD src1_sel:WORD_0
	v_cmp_lt_i32_e32 vcc, v194, v206
	v_lshl_add_u32 v246, v240, 8, v253
	global_load_dwordx4 v[216:219], v246, s[12:13]
	v_cndmask_b32_sdwa v240, v1, v249, vcc dst_sel:DWORD dst_unused:UNUSED_PAD src0_sel:DWORD src1_sel:WORD_1
	v_cmp_lt_i32_e32 vcc, v157, v206
	v_lshl_add_u32 v247, v240, 8, v253
	global_load_dwordx4 v[220:223], v247, s[12:13]
	v_cndmask_b32_sdwa v240, v1, v250, vcc dst_sel:DWORD dst_unused:UNUSED_PAD src0_sel:DWORD src1_sel:WORD_0
	v_cmp_lt_i32_e32 vcc, v195, v206
	v_lshl_add_u32 v244, v240, 8, v253
	global_load_dwordx4 v[224:227], v244, s[12:13]
	v_cndmask_b32_sdwa v240, v1, v250, vcc dst_sel:DWORD dst_unused:UNUSED_PAD src0_sel:DWORD src1_sel:WORD_1
	v_cmp_lt_i32_e32 vcc, v196, v206
	v_lshl_add_u32 v245, v240, 8, v253
	global_load_dwordx4 v[228:231], v245, s[12:13]
	v_cndmask_b32_sdwa v240, v1, v251, vcc dst_sel:DWORD dst_unused:UNUSED_PAD src0_sel:DWORD src1_sel:WORD_0
	v_cmp_lt_i32_e32 vcc, v197, v206
	v_lshl_add_u32 v246, v240, 8, v253
	global_load_dwordx4 v[232:235], v246, s[12:13]
	v_cndmask_b32_sdwa v240, v1, v251, vcc dst_sel:DWORD dst_unused:UNUSED_PAD src0_sel:DWORD src1_sel:WORD_1
	v_lshl_add_u32 v247, v240, 8, v253
	global_load_dwordx4 v[236:239], v247, s[12:13]
	v_cmp_lt_i32_e32 vcc, 0, v131
	s_nop 1
	v_cndmask_b32_e32 v140, v1, v18, vcc
	v_lshl_add_u32 v142, v140, 8, v134
	global_load_dwordx4 v[82:85], v142, s[14:15]
	global_load_dwordx4 v[86:89], v142, s[14:15] offset:64
	global_load_dwordx4 v[90:93], v142, s[14:15] offset:128
	global_load_dwordx4 v[94:97], v142, s[14:15] offset:192
	v_cmp_lt_i32_e32 vcc, 16, v131
	s_nop 1
	v_cndmask_b32_e32 v140, v1, v22, vcc
	v_lshl_add_u32 v144, v140, 8, v134
	global_load_dwordx4 v[98:101], v144, s[14:15]
	global_load_dwordx4 v[102:105], v144, s[14:15] offset:64
	global_load_dwordx4 v[106:109], v144, s[14:15] offset:128
	global_load_dwordx4 v[110:113], v144, s[14:15] offset:192
	v_cmp_lt_i32_e32 vcc, 32, v131
	s_nop 1
	v_cndmask_b32_e32 v140, v1, v26, vcc
	v_lshl_add_u32 v142, v140, 8, v134
	global_load_dwordx4 v[114:117], v142, s[14:15]
	global_load_dwordx4 v[118:121], v142, s[14:15] offset:64
	global_load_dwordx4 v[122:125], v142, s[14:15] offset:128
	global_load_dwordx4 v[126:129], v142, s[14:15] offset:192
	s_waitcnt vmcnt(8)
; #define MFMA4(a, b, c)  __builtin_amdgcn_mfma_f32_4x4x4bf16_1k((a), (b), (c), 0, 0, 0)
; DI void dsa_item(const Params& p, int b, int blk) {
;     ...
;     #pragma unroll
;     for (int rd = 0; rd < 4; ++rd) {
;       if (rd < 3) {
;         const int ks = (rd + 1) * 64 + lane;
;         valid[rd + 1] = ks < cnt;
;         const int idx = valid[rd + 1] ? (int)sel[qq * 256 + ks] : 0;
;         const u16* kptr = Ak + (rowbase + idx) * 128;
;         #pragma unroll
;         for (int c = 0; c < 8; ++c) { ka[(rd + 1) & 1][c] = ldg<bf16x8>(kptr + c * 8); kb[(rd + 1) & 1][c] = ldg<bf16x8>(kptr + 64 + c * 8); }
;       }
;       f32x4 c0 = {0.f, 0.f, 0.f, 0.f}, c1 = {0.f, 0.f, 0.f, 0.f};
;       #pragma unroll
;       for (int c = 0; c < 8; ++c) {
;         const bf16x8 kav = ka[rd & 1][c], kbv = kb[rd & 1][c];
;         s16x4 qlo = {qa[c][0], qa[c][1], qa[c][2], qa[c][3]}, qhi = {qa[c][4], qa[c][5], qa[c][6], qa[c][7]};
;         s16x4 klo = {kav[0], kav[1], kav[2], kav[3]}, khi = {kav[4], kav[5], kav[6], kav[7]};
;         c0 = MFMA4(qlo, klo, c0); c0 = MFMA4(qhi, khi, c0);
;         s16x4 rlo = {qb[c][0], qb[c][1], qb[c][2], qb[c][3]}, rhi = {qb[c][4], qb[c][5], qb[c][6], qb[c][7]};
;         s16x4 llo = {kbv[0], kbv[1], kbv[2], kbv[3]}, lhi = {kbv[4], kbv[5], kbv[6], kbv[7]};
;         c1 = MFMA4(rlo, llo, c1); c1 = MFMA4(rhi, lhi, c1);
;       }
	v_mfma_f32_16x16x32_bf16 v[18:21], v[82:85], v[2:5], 0
	v_mfma_f32_16x16x32_bf16 v[18:21], v[86:89], v[6:9], v[18:21]
	v_mfma_f32_16x16x32_bf16 v[18:21], v[90:93], v[10:13], v[18:21]
	v_mfma_f32_16x16x32_bf16 v[18:21], v[94:97], v[14:17], v[18:21]
	v_cmp_lt_i32_e32 vcc, 48, v131
	s_nop 1
	v_cndmask_b32_e32 v140, v1, v30, vcc
	v_lshl_add_u32 v144, v140, 8, v134
	global_load_dwordx4 v[82:85], v144, s[14:15]
	global_load_dwordx4 v[86:89], v144, s[14:15] offset:64
	global_load_dwordx4 v[90:93], v144, s[14:15] offset:128
	global_load_dwordx4 v[94:97], v144, s[14:15] offset:192
	s_waitcnt vmcnt(8)
	v_mfma_f32_16x16x32_bf16 v[22:25], v[98:101], v[2:5], 0
	v_mfma_f32_16x16x32_bf16 v[22:25], v[102:105], v[6:9], v[22:25]
	v_mfma_f32_16x16x32_bf16 v[22:25], v[106:109], v[10:13], v[22:25]
	v_mfma_f32_16x16x32_bf16 v[22:25], v[110:113], v[14:17], v[22:25]
	v_cmp_lt_i32_e32 vcc, 64, v131
	s_nop 1
	v_cndmask_b32_e32 v140, v1, v34, vcc
	v_lshl_add_u32 v142, v140, 8, v134
	global_load_dwordx4 v[98:101], v142, s[14:15]
	global_load_dwordx4 v[102:105], v142, s[14:15] offset:64
	global_load_dwordx4 v[106:109], v142, s[14:15] offset:128
	global_load_dwordx4 v[110:113], v142, s[14:15] offset:192
	s_waitcnt vmcnt(8)
	v_mfma_f32_16x16x32_bf16 v[26:29], v[114:117], v[2:5], 0
	v_mfma_f32_16x16x32_bf16 v[26:29], v[118:121], v[6:9], v[26:29]
	v_mfma_f32_16x16x32_bf16 v[26:29], v[122:125], v[10:13], v[26:29]
	v_mfma_f32_16x16x32_bf16 v[26:29], v[126:129], v[14:17], v[26:29]
	v_cmp_lt_i32_e32 vcc, 0x50, v131
	s_nop 1
	v_cndmask_b32_e32 v140, v1, v38, vcc
	v_lshl_add_u32 v144, v140, 8, v134
	global_load_dwordx4 v[114:117], v144, s[14:15]
	global_load_dwordx4 v[118:121], v144, s[14:15] offset:64
	global_load_dwordx4 v[122:125], v144, s[14:15] offset:128
	global_load_dwordx4 v[126:129], v144, s[14:15] offset:192
	s_waitcnt vmcnt(8)
	v_mfma_f32_16x16x32_bf16 v[30:33], v[82:85], v[2:5], 0
	v_mfma_f32_16x16x32_bf16 v[30:33], v[86:89], v[6:9], v[30:33]
	v_mfma_f32_16x16x32_bf16 v[30:33], v[90:93], v[10:13], v[30:33]
	v_mfma_f32_16x16x32_bf16 v[30:33], v[94:97], v[14:17], v[30:33]
	v_cmp_lt_i32_e32 vcc, 0x60, v131
	s_nop 1
	v_cndmask_b32_e32 v140, v1, v42, vcc
	v_lshl_add_u32 v142, v140, 8, v134
	global_load_dwordx4 v[82:85], v142, s[14:15]
	global_load_dwordx4 v[86:89], v142, s[14:15] offset:64
	global_load_dwordx4 v[90:93], v142, s[14:15] offset:128
	global_load_dwordx4 v[94:97], v142, s[14:15] offset:192
	s_waitcnt vmcnt(8)
	v_mfma_f32_16x16x32_bf16 v[34:37], v[98:101], v[2:5], 0
	v_mfma_f32_16x16x32_bf16 v[34:37], v[102:105], v[6:9], v[34:37]
	v_mfma_f32_16x16x32_bf16 v[34:37], v[106:109], v[10:13], v[34:37]
	v_mfma_f32_16x16x32_bf16 v[34:37], v[110:113], v[14:17], v[34:37]
	v_cmp_lt_i32_e32 vcc, 0x70, v131
	s_nop 1
	v_cndmask_b32_e32 v140, v1, v46, vcc
	v_lshl_add_u32 v144, v140, 8, v134
	global_load_dwordx4 v[98:101], v144, s[14:15]
	global_load_dwordx4 v[102:105], v144, s[14:15] offset:64
	global_load_dwordx4 v[106:109], v144, s[14:15] offset:128
	global_load_dwordx4 v[110:113], v144, s[14:15] offset:192
	s_waitcnt vmcnt(8)
	v_mfma_f32_16x16x32_bf16 v[38:41], v[114:117], v[2:5], 0
	v_mfma_f32_16x16x32_bf16 v[38:41], v[118:121], v[6:9], v[38:41]
	v_mfma_f32_16x16x32_bf16 v[38:41], v[122:125], v[10:13], v[38:41]
	v_mfma_f32_16x16x32_bf16 v[38:41], v[126:129], v[14:17], v[38:41]
	v_cmp_lt_i32_e32 vcc, 0x80, v131
	s_nop 1
	v_cndmask_b32_e32 v140, v1, v50, vcc
	v_lshl_add_u32 v142, v140, 8, v134
	global_load_dwordx4 v[114:117], v142, s[14:15]
	global_load_dwordx4 v[118:121], v142, s[14:15] offset:64
	global_load_dwordx4 v[122:125], v142, s[14:15] offset:128
	global_load_dwordx4 v[126:129], v142, s[14:15] offset:192
	s_waitcnt vmcnt(8)
	v_mfma_f32_16x16x32_bf16 v[42:45], v[82:85], v[2:5], 0
	v_mfma_f32_16x16x32_bf16 v[42:45], v[86:89], v[6:9], v[42:45]
	v_mfma_f32_16x16x32_bf16 v[42:45], v[90:93], v[10:13], v[42:45]
	v_mfma_f32_16x16x32_bf16 v[42:45], v[94:97], v[14:17], v[42:45]
	v_cmp_lt_i32_e32 vcc, 0x90, v131
	s_nop 1
	v_cndmask_b32_e32 v140, v1, v54, vcc
	v_lshl_add_u32 v144, v140, 8, v134
	global_load_dwordx4 v[82:85], v144, s[14:15]
	global_load_dwordx4 v[86:89], v144, s[14:15] offset:64
	global_load_dwordx4 v[90:93], v144, s[14:15] offset:128
	global_load_dwordx4 v[94:97], v144, s[14:15] offset:192
	s_waitcnt vmcnt(8)
	v_mfma_f32_16x16x32_bf16 v[46:49], v[98:101], v[2:5], 0
	v_mfma_f32_16x16x32_bf16 v[46:49], v[102:105], v[6:9], v[46:49]
	v_mfma_f32_16x16x32_bf16 v[46:49], v[106:109], v[10:13], v[46:49]
	v_mfma_f32_16x16x32_bf16 v[46:49], v[110:113], v[14:17], v[46:49]
	v_cmp_lt_i32_e32 vcc, 0xa0, v131
	s_nop 1
	v_cndmask_b32_e32 v140, v1, v58, vcc
	v_lshl_add_u32 v142, v140, 8, v134
	global_load_dwordx4 v[98:101], v142, s[14:15]
	global_load_dwordx4 v[102:105], v142, s[14:15] offset:64
	global_load_dwordx4 v[106:109], v142, s[14:15] offset:128
	global_load_dwordx4 v[110:113], v142, s[14:15] offset:192
	s_waitcnt vmcnt(8)
	v_mfma_f32_16x16x32_bf16 v[50:53], v[114:117], v[2:5], 0
	v_mfma_f32_16x16x32_bf16 v[50:53], v[118:121], v[6:9], v[50:53]
	v_mfma_f32_16x16x32_bf16 v[50:53], v[122:125], v[10:13], v[50:53]
	v_mfma_f32_16x16x32_bf16 v[50:53], v[126:129], v[14:17], v[50:53]
	v_cmp_lt_i32_e32 vcc, 0xb0, v131
	s_nop 1
	v_cndmask_b32_e32 v140, v1, v62, vcc
	v_lshl_add_u32 v144, v140, 8, v134
	global_load_dwordx4 v[114:117], v144, s[14:15]
	global_load_dwordx4 v[118:121], v144, s[14:15] offset:64
	global_load_dwordx4 v[122:125], v144, s[14:15] offset:128
	global_load_dwordx4 v[126:129], v144, s[14:15] offset:192
	s_waitcnt vmcnt(8)
; #define MFMA4(a, b, c)  __builtin_amdgcn_mfma_f32_4x4x4bf16_1k((a), (b), (c), 0, 0, 0)
; DI void dsa_item(const Params& p, int b, int blk) {
;     ...
;     #pragma unroll
;     for (int rd = 0; rd < 4; ++rd) {
;       if (rd < 3) {
;         const int ks = (rd + 1) * 64 + lane;
;         valid[rd + 1] = ks < cnt;
;         const int idx = valid[rd + 1] ? (int)sel[qq * 256 + ks] : 0;
;         const u16* kptr = Ak + (rowbase + idx) * 128;
;         #pragma unroll
;         for (int c = 0; c < 8; ++c) { ka[(rd + 1) & 1][c] = ldg<bf16x8>(kptr + c * 8); kb[(rd + 1) & 1][c] = ldg<bf16x8>(kptr + 64 + c * 8); }
;       }
;       f32x4 c0 = {0.f, 0.f, 0.f, 0.f}, c1 = {0.f, 0.f, 0.f, 0.f};
;       #pragma unroll
;       for (int c = 0; c < 8; ++c) {
;         const bf16x8 kav = ka[rd & 1][c], kbv = kb[rd & 1][c];
;         s16x4 qlo = {qa[c][0], qa[c][1], qa[c][2], qa[c][3]}, qhi = {qa[c][4], qa[c][5], qa[c][6], qa[c][7]};
;         s16x4 klo = {kav[0], kav[1], kav[2], kav[3]}, khi = {kav[4], kav[5], kav[6], kav[7]};
;         c0 = MFMA4(qlo, klo, c0); c0 = MFMA4(qhi, khi, c0);
;         s16x4 rlo = {qb[c][0], qb[c][1], qb[c][2], qb[c][3]}, rhi = {qb[c][4], qb[c][5], qb[c][6], qb[c][7]};
;         s16x4 llo = {kbv[0], kbv[1], kbv[2], kbv[3]}, lhi = {kbv[4], kbv[5], kbv[6], kbv[7]};
;         c1 = MFMA4(rlo, llo, c1); c1 = MFMA4(rhi, lhi, c1);
;       }
;       #pragma unroll
;       for (int m = 0; m < 4; ++m) { sc[rd][m] = valid[rd] ? c0[m] * SSC : -1e30f; sc[rd][4 + m] = valid[rd] ? c1[m] * SSC : -1e30f; }
;     }
;     ...
;       if (kc < 7) {
;         const u32x4 si = *(const u32x4*)(sel + qq * 256 + (kc + 1) * 32 + 8 * g16);
;         #pragma unroll
;         for (int j = 0; j < 8; ++j) {
;           const int ks = (kc + 1) * 32 + 8 * g16 + j;
;           const int idx = ks < cnt ? (int)((si[j >> 1] >> (16 * (j & 1))) & 0xffffu) : 0;
;           vr[j] = ldg<u32x4>(Av + (rowbase + idx) * 128 + n16 * 8);
;         }
;       }
	v_mfma_f32_16x16x32_bf16 v[54:57], v[82:85], v[2:5], 0
	v_mfma_f32_16x16x32_bf16 v[54:57], v[86:89], v[6:9], v[54:57]
	v_mfma_f32_16x16x32_bf16 v[54:57], v[90:93], v[10:13], v[54:57]
	v_mfma_f32_16x16x32_bf16 v[54:57], v[94:97], v[14:17], v[54:57]
	v_cmp_lt_i32_e32 vcc, 0xc0, v131
	s_nop 1
	v_cndmask_b32_e32 v140, v1, v66, vcc
	v_lshl_add_u32 v142, v140, 8, v134
	global_load_dwordx4 v[82:85], v142, s[14:15]
	global_load_dwordx4 v[86:89], v142, s[14:15] offset:64
	global_load_dwordx4 v[90:93], v142, s[14:15] offset:128
	global_load_dwordx4 v[94:97], v142, s[14:15] offset:192
	s_waitcnt vmcnt(8)
	v_mfma_f32_16x16x32_bf16 v[58:61], v[98:101], v[2:5], 0
	v_mfma_f32_16x16x32_bf16 v[58:61], v[102:105], v[6:9], v[58:61]
	v_mfma_f32_16x16x32_bf16 v[58:61], v[106:109], v[10:13], v[58:61]
	v_mfma_f32_16x16x32_bf16 v[58:61], v[110:113], v[14:17], v[58:61]
	v_cmp_lt_i32_e32 vcc, 0xd0, v131
	s_nop 1
	v_cndmask_b32_e32 v140, v1, v70, vcc
	v_lshl_add_u32 v144, v140, 8, v134
	global_load_dwordx4 v[98:101], v144, s[14:15]
	global_load_dwordx4 v[102:105], v144, s[14:15] offset:64
	global_load_dwordx4 v[106:109], v144, s[14:15] offset:128
	global_load_dwordx4 v[110:113], v144, s[14:15] offset:192
	s_waitcnt vmcnt(8)
	v_mfma_f32_16x16x32_bf16 v[62:65], v[114:117], v[2:5], 0
	v_mfma_f32_16x16x32_bf16 v[62:65], v[118:121], v[6:9], v[62:65]
	v_mfma_f32_16x16x32_bf16 v[62:65], v[122:125], v[10:13], v[62:65]
	v_mfma_f32_16x16x32_bf16 v[62:65], v[126:129], v[14:17], v[62:65]
	v_cmp_lt_i32_e32 vcc, 0xe0, v131
	s_nop 1
	v_cndmask_b32_e32 v140, v1, v74, vcc
	v_lshl_add_u32 v142, v140, 8, v134
	global_load_dwordx4 v[114:117], v142, s[14:15]
	global_load_dwordx4 v[118:121], v142, s[14:15] offset:64
	global_load_dwordx4 v[122:125], v142, s[14:15] offset:128
	global_load_dwordx4 v[126:129], v142, s[14:15] offset:192
	s_waitcnt vmcnt(8)
	v_mfma_f32_16x16x32_bf16 v[66:69], v[82:85], v[2:5], 0
	v_mfma_f32_16x16x32_bf16 v[66:69], v[86:89], v[6:9], v[66:69]
	v_mfma_f32_16x16x32_bf16 v[66:69], v[90:93], v[10:13], v[66:69]
	v_mfma_f32_16x16x32_bf16 v[66:69], v[94:97], v[14:17], v[66:69]
	v_cmp_lt_i32_e32 vcc, 0xf0, v131
	s_nop 1
	v_cndmask_b32_e32 v140, v1, v78, vcc
	v_lshl_add_u32 v144, v140, 8, v134
	global_load_dwordx4 v[82:85], v144, s[14:15]
	global_load_dwordx4 v[86:89], v144, s[14:15] offset:64
	global_load_dwordx4 v[90:93], v144, s[14:15] offset:128
	global_load_dwordx4 v[94:97], v144, s[14:15] offset:192
	s_waitcnt vmcnt(8)
	v_mfma_f32_16x16x32_bf16 v[70:73], v[98:101], v[2:5], 0
	v_mfma_f32_16x16x32_bf16 v[70:73], v[102:105], v[6:9], v[70:73]
	v_mfma_f32_16x16x32_bf16 v[70:73], v[106:109], v[10:13], v[70:73]
	v_mfma_f32_16x16x32_bf16 v[70:73], v[110:113], v[14:17], v[70:73]
	s_waitcnt vmcnt(4)
	v_mfma_f32_16x16x32_bf16 v[74:77], v[114:117], v[2:5], 0
	v_mfma_f32_16x16x32_bf16 v[74:77], v[118:121], v[6:9], v[74:77]
	v_mfma_f32_16x16x32_bf16 v[74:77], v[122:125], v[10:13], v[74:77]
	v_mfma_f32_16x16x32_bf16 v[74:77], v[126:129], v[14:17], v[74:77]
	s_waitcnt vmcnt(0)
	v_mfma_f32_16x16x32_bf16 v[78:81], v[82:85], v[2:5], 0
	v_mfma_f32_16x16x32_bf16 v[78:81], v[86:89], v[6:9], v[78:81]
	v_mfma_f32_16x16x32_bf16 v[78:81], v[90:93], v[10:13], v[78:81]
	v_mfma_f32_16x16x32_bf16 v[78:81], v[94:97], v[14:17], v[78:81]
	v_mov_b32_e32 v8, v132
	v_mov_b32_e32 v9, v136
	v_mov_b32_e32 v10, v137
	ds_read_b128 v[12:15], v242 offset:64
	s_waitcnt lgkmcnt(0)
	v_add_u32_e32 v243, 0xffffffe0, v206
	v_cmp_lt_i32_e32 vcc, v156, v243
	s_nop 1
	v_cndmask_b32_sdwa v240, v1, v12, vcc dst_sel:DWORD dst_unused:UNUSED_PAD src0_sel:DWORD src1_sel:WORD_0
	v_cmp_lt_i32_e32 vcc, v192, v243
	v_lshl_add_u32 v244, v240, 8, v253
	global_load_dwordx4 v[106:109], v244, s[12:13]
	v_cndmask_b32_sdwa v240, v1, v12, vcc dst_sel:DWORD dst_unused:UNUSED_PAD src0_sel:DWORD src1_sel:WORD_1
	v_cmp_lt_i32_e32 vcc, v193, v243
	v_lshl_add_u32 v245, v240, 8, v253
	global_load_dwordx4 v[110:113], v245, s[12:13]
	v_cndmask_b32_sdwa v240, v1, v13, vcc dst_sel:DWORD dst_unused:UNUSED_PAD src0_sel:DWORD src1_sel:WORD_0
	v_cmp_lt_i32_e32 vcc, v194, v243
	v_lshl_add_u32 v246, v240, 8, v253
	global_load_dwordx4 v[114:117], v246, s[12:13]
	v_cndmask_b32_sdwa v240, v1, v13, vcc dst_sel:DWORD dst_unused:UNUSED_PAD src0_sel:DWORD src1_sel:WORD_1
	v_cmp_lt_i32_e32 vcc, v157, v243
	v_lshl_add_u32 v247, v240, 8, v253
	global_load_dwordx4 v[118:121], v247, s[12:13]
	v_cndmask_b32_sdwa v240, v1, v14, vcc dst_sel:DWORD dst_unused:UNUSED_PAD src0_sel:DWORD src1_sel:WORD_0
	v_cmp_lt_i32_e32 vcc, v195, v243
	v_lshl_add_u32 v244, v240, 8, v253
	global_load_dwordx4 v[122:125], v244, s[12:13]
	v_cndmask_b32_sdwa v240, v1, v14, vcc dst_sel:DWORD dst_unused:UNUSED_PAD src0_sel:DWORD src1_sel:WORD_1
	v_cmp_lt_i32_e32 vcc, v196, v243
	v_lshl_add_u32 v245, v240, 8, v253
	global_load_dwordx4 v[126:129], v245, s[12:13]
	v_cndmask_b32_sdwa v240, v1, v15, vcc dst_sel:DWORD dst_unused:UNUSED_PAD src0_sel:DWORD src1_sel:WORD_0
	v_cmp_lt_i32_e32 vcc, v197, v243
	v_lshl_add_u32 v246, v240, 8, v253
	global_load_dwordx4 v[130:133], v246, s[12:13]
	v_cndmask_b32_sdwa v240, v1, v15, vcc dst_sel:DWORD dst_unused:UNUSED_PAD src0_sel:DWORD src1_sel:WORD_1
	v_lshl_add_u32 v247, v240, 8, v253
	global_load_dwordx4 v[134:137], v247, s[12:13]
	v_mul_f32_e32 v18, 0x3e38aa3b, v18
	v_mul_f32_e32 v19, 0x3e38aa3b, v19
	v_mul_f32_e32 v20, 0x3e38aa3b, v20
	v_mul_f32_e32 v21, 0x3e38aa3b, v21
	v_mul_f32_e32 v22, 0x3e38aa3b, v22
	v_mul_f32_e32 v23, 0x3e38aa3b, v23
	v_mul_f32_e32 v24, 0x3e38aa3b, v24
	v_mul_f32_e32 v25, 0x3e38aa3b, v25
	v_mul_f32_e32 v26, 0x3e38aa3b, v26
	v_mul_f32_e32 v27, 0x3e38aa3b, v27
	v_mul_f32_e32 v28, 0x3e38aa3b, v28
	v_mul_f32_e32 v29, 0x3e38aa3b, v29
; DI void dsa_item(const Params& p, int b, int blk) {
;     ...
;       for (int m = 0; m < 4; ++m) { sc[rd][m] = valid[rd] ? c0[m] * SSC : -1e30f; sc[rd][4 + m] = valid[rd] ? c1[m] * SSC : -1e30f; }
	v_mul_f32_e32 v30, 0x3e38aa3b, v30
	v_mul_f32_e32 v31, 0x3e38aa3b, v31
	v_mul_f32_e32 v32, 0x3e38aa3b, v32
	v_mul_f32_e32 v33, 0x3e38aa3b, v33
	v_mul_f32_e32 v34, 0x3e38aa3b, v34
	v_mul_f32_e32 v35, 0x3e38aa3b, v35
	v_mul_f32_e32 v36, 0x3e38aa3b, v36
	v_mul_f32_e32 v37, 0x3e38aa3b, v37
	v_mul_f32_e32 v38, 0x3e38aa3b, v38
	v_mul_f32_e32 v39, 0x3e38aa3b, v39
	v_mul_f32_e32 v40, 0x3e38aa3b, v40
	v_mul_f32_e32 v41, 0x3e38aa3b, v41
	v_mul_f32_e32 v42, 0x3e38aa3b, v42
	v_mul_f32_e32 v43, 0x3e38aa3b, v43
	v_mul_f32_e32 v44, 0x3e38aa3b, v44
	v_mul_f32_e32 v45, 0x3e38aa3b, v45
	v_mul_f32_e32 v46, 0x3e38aa3b, v46
	v_mul_f32_e32 v47, 0x3e38aa3b, v47
	v_mul_f32_e32 v48, 0x3e38aa3b, v48
	v_mul_f32_e32 v49, 0x3e38aa3b, v49
	v_mul_f32_e32 v50, 0x3e38aa3b, v50
	v_mul_f32_e32 v51, 0x3e38aa3b, v51
	v_mul_f32_e32 v52, 0x3e38aa3b, v52
	v_mul_f32_e32 v53, 0x3e38aa3b, v53
	v_mul_f32_e32 v54, 0x3e38aa3b, v54
	v_mul_f32_e32 v55, 0x3e38aa3b, v55
	v_mul_f32_e32 v56, 0x3e38aa3b, v56
	v_mul_f32_e32 v57, 0x3e38aa3b, v57
	v_mul_f32_e32 v58, 0x3e38aa3b, v58
	v_mul_f32_e32 v59, 0x3e38aa3b, v59
	v_mul_f32_e32 v60, 0x3e38aa3b, v60
	v_mul_f32_e32 v61, 0x3e38aa3b, v61
	v_mul_f32_e32 v62, 0x3e38aa3b, v62
	v_mul_f32_e32 v63, 0x3e38aa3b, v63
	v_mul_f32_e32 v64, 0x3e38aa3b, v64
	v_mul_f32_e32 v65, 0x3e38aa3b, v65
	v_mul_f32_e32 v66, 0x3e38aa3b, v66
	v_mul_f32_e32 v67, 0x3e38aa3b, v67
	v_mul_f32_e32 v68, 0x3e38aa3b, v68
	v_mul_f32_e32 v69, 0x3e38aa3b, v69
	v_mul_f32_e32 v70, 0x3e38aa3b, v70
	v_mul_f32_e32 v71, 0x3e38aa3b, v71
	v_mul_f32_e32 v72, 0x3e38aa3b, v72
	v_mul_f32_e32 v73, 0x3e38aa3b, v73
	v_mul_f32_e32 v74, 0x3e38aa3b, v74
	v_mul_f32_e32 v75, 0x3e38aa3b, v75
	v_mul_f32_e32 v76, 0x3e38aa3b, v76
	v_mul_f32_e32 v77, 0x3e38aa3b, v77
	v_mul_f32_e32 v78, 0x3e38aa3b, v78
	v_mul_f32_e32 v79, 0x3e38aa3b, v79
	v_mul_f32_e32 v80, 0x3e38aa3b, v80
	v_mul_f32_e32 v81, 0x3e38aa3b, v81
	s_cmpk_ge_i32 s100, 0x100
	s_cbranch_scc1 .Lqk_nomask
	v_cmp_lt_i32_e32 vcc, 0, v8
	s_nop 1
	v_cndmask_b32_e32 v18, v139, v18, vcc
	v_cmp_lt_i32_e32 vcc, 1, v8
	s_nop 1
	v_cndmask_b32_e32 v19, v139, v19, vcc
	v_cmp_lt_i32_e32 vcc, 2, v8
	s_nop 1
	v_cndmask_b32_e32 v20, v139, v20, vcc
	v_cmp_lt_i32_e32 vcc, 3, v8
	s_nop 1
	v_cndmask_b32_e32 v21, v139, v21, vcc
	v_cmp_lt_i32_e32 vcc, 16, v8
	s_nop 1
	v_cndmask_b32_e32 v22, v139, v22, vcc
	v_cmp_lt_i32_e32 vcc, 17, v8
	s_nop 1
	v_cndmask_b32_e32 v23, v139, v23, vcc
	v_cmp_lt_i32_e32 vcc, 18, v8
	s_nop 1
	v_cndmask_b32_e32 v24, v139, v24, vcc
	v_cmp_lt_i32_e32 vcc, 19, v8
	s_nop 1
	v_cndmask_b32_e32 v25, v139, v25, vcc
	v_cmp_lt_i32_e32 vcc, 32, v8
	s_nop 1
	v_cndmask_b32_e32 v26, v139, v26, vcc
	v_cmp_lt_i32_e32 vcc, 33, v8
	s_nop 1
	v_cndmask_b32_e32 v27, v139, v27, vcc
	v_cmp_lt_i32_e32 vcc, 34, v8
	s_nop 1
	v_cndmask_b32_e32 v28, v139, v28, vcc
	v_cmp_lt_i32_e32 vcc, 35, v8
	s_nop 1
	v_cndmask_b32_e32 v29, v139, v29, vcc
	v_cmp_lt_i32_e32 vcc, 48, v8
	s_nop 1
	v_cndmask_b32_e32 v30, v139, v30, vcc
	v_cmp_lt_i32_e32 vcc, 49, v8
	s_nop 1
	v_cndmask_b32_e32 v31, v139, v31, vcc
	v_cmp_lt_i32_e32 vcc, 50, v8
	s_nop 1
	v_cndmask_b32_e32 v32, v139, v32, vcc
	v_cmp_lt_i32_e32 vcc, 51, v8
	s_nop 1
	v_cndmask_b32_e32 v33, v139, v33, vcc
	v_cmp_lt_i32_e32 vcc, 64, v8
	s_nop 1
	v_cndmask_b32_e32 v34, v139, v34, vcc
	v_cmp_lt_i32_e32 vcc, 0x41, v8
	s_nop 1
	v_cndmask_b32_e32 v35, v139, v35, vcc
	v_cmp_lt_i32_e32 vcc, 0x42, v8
	s_nop 1
	v_cndmask_b32_e32 v36, v139, v36, vcc
	v_cmp_lt_i32_e32 vcc, 0x43, v8
	s_nop 1
	v_cndmask_b32_e32 v37, v139, v37, vcc
	v_cmp_lt_i32_e32 vcc, 0x50, v8
	s_nop 1
	v_cndmask_b32_e32 v38, v139, v38, vcc
	v_cmp_lt_i32_e32 vcc, 0x51, v8
	s_nop 1
	v_cndmask_b32_e32 v39, v139, v39, vcc
	v_cmp_lt_i32_e32 vcc, 0x52, v8
	s_nop 1
	v_cndmask_b32_e32 v40, v139, v40, vcc
	v_cmp_lt_i32_e32 vcc, 0x53, v8
	s_nop 1
	v_cndmask_b32_e32 v41, v139, v41, vcc
	v_cmp_lt_i32_e32 vcc, 0x60, v8
	s_nop 1
	v_cndmask_b32_e32 v42, v139, v42, vcc
	v_cmp_lt_i32_e32 vcc, 0x61, v8
	s_nop 1
	v_cndmask_b32_e32 v43, v139, v43, vcc
	v_cmp_lt_i32_e32 vcc, 0x62, v8
	s_nop 1
	v_cndmask_b32_e32 v44, v139, v44, vcc
	v_cmp_lt_i32_e32 vcc, 0x63, v8
	s_nop 1
	v_cndmask_b32_e32 v45, v139, v45, vcc
	v_cmp_lt_i32_e32 vcc, 0x70, v8
	s_nop 1
	v_cndmask_b32_e32 v46, v139, v46, vcc
	v_cmp_lt_i32_e32 vcc, 0x71, v8
	s_nop 1
	v_cndmask_b32_e32 v47, v139, v47, vcc
	v_cmp_lt_i32_e32 vcc, 0x72, v8
	s_nop 1
	v_cndmask_b32_e32 v48, v139, v48, vcc
	v_cmp_lt_i32_e32 vcc, 0x73, v8
	s_nop 1
	v_cndmask_b32_e32 v49, v139, v49, vcc
	v_cmp_lt_i32_e32 vcc, 0x80, v8
	s_nop 1
	v_cndmask_b32_e32 v50, v139, v50, vcc
	v_cmp_lt_i32_e32 vcc, 0x81, v8
	s_nop 1
	v_cndmask_b32_e32 v51, v139, v51, vcc
	v_cmp_lt_i32_e32 vcc, 0x82, v8
	s_nop 1
	v_cndmask_b32_e32 v52, v139, v52, vcc
	v_cmp_lt_i32_e32 vcc, 0x83, v8
	s_nop 1
	v_cndmask_b32_e32 v53, v139, v53, vcc
	v_cmp_lt_i32_e32 vcc, 0x90, v8
	s_nop 1
	v_cndmask_b32_e32 v54, v139, v54, vcc
	v_cmp_lt_i32_e32 vcc, 0x91, v8
	s_nop 1
	v_cndmask_b32_e32 v55, v139, v55, vcc
	v_cmp_lt_i32_e32 vcc, 0x92, v8
	s_nop 1
	v_cndmask_b32_e32 v56, v139, v56, vcc
	v_cmp_lt_i32_e32 vcc, 0x93, v8
	s_nop 1
	v_cndmask_b32_e32 v57, v139, v57, vcc
	v_cmp_lt_i32_e32 vcc, 0xa0, v8
	s_nop 1
	v_cndmask_b32_e32 v58, v139, v58, vcc
	v_cmp_lt_i32_e32 vcc, 0xa1, v8
	s_nop 1
	v_cndmask_b32_e32 v59, v139, v59, vcc
	v_cmp_lt_i32_e32 vcc, 0xa2, v8
	s_nop 1
	v_cndmask_b32_e32 v60, v139, v60, vcc
	v_cmp_lt_i32_e32 vcc, 0xa3, v8
	s_nop 1
	v_cndmask_b32_e32 v61, v139, v61, vcc
	v_cmp_lt_i32_e32 vcc, 0xb0, v8
	s_nop 1
	v_cndmask_b32_e32 v62, v139, v62, vcc
	v_cmp_lt_i32_e32 vcc, 0xb1, v8
	s_nop 1
	v_cndmask_b32_e32 v63, v139, v63, vcc
	v_cmp_lt_i32_e32 vcc, 0xb2, v8
	s_nop 1
	v_cndmask_b32_e32 v64, v139, v64, vcc
	v_cmp_lt_i32_e32 vcc, 0xb3, v8
	s_nop 1
	v_cndmask_b32_e32 v65, v139, v65, vcc
	v_cmp_lt_i32_e32 vcc, 0xc0, v8
	s_nop 1
	v_cndmask_b32_e32 v66, v139, v66, vcc
	v_cmp_lt_i32_e32 vcc, 0xc1, v8
	s_nop 1
	v_cndmask_b32_e32 v67, v139, v67, vcc
	v_cmp_lt_i32_e32 vcc, 0xc2, v8
	s_nop 1
	v_cndmask_b32_e32 v68, v139, v68, vcc
	v_cmp_lt_i32_e32 vcc, 0xc3, v8
	s_nop 1
	v_cndmask_b32_e32 v69, v139, v69, vcc
	v_cmp_lt_i32_e32 vcc, 0xd0, v8
	s_nop 1
	v_cndmask_b32_e32 v70, v139, v70, vcc
	v_cmp_lt_i32_e32 vcc, 0xd1, v8
	s_nop 1
	v_cndmask_b32_e32 v71, v139, v71, vcc
	v_cmp_lt_i32_e32 vcc, 0xd2, v8
	s_nop 1
	v_cndmask_b32_e32 v72, v139, v72, vcc
	v_cmp_lt_i32_e32 vcc, 0xd3, v8
	s_nop 1
	v_cndmask_b32_e32 v73, v139, v73, vcc
	v_cmp_lt_i32_e32 vcc, 0xe0, v8
	s_nop 1
	v_cndmask_b32_e32 v74, v139, v74, vcc
	v_cmp_lt_i32_e32 vcc, 0xe1, v8
	s_nop 1
	v_cndmask_b32_e32 v75, v139, v75, vcc
	v_cmp_lt_i32_e32 vcc, 0xe2, v8
	s_nop 1
	v_cndmask_b32_e32 v76, v139, v76, vcc
	v_cmp_lt_i32_e32 vcc, 0xe3, v8
	s_nop 1
	v_cndmask_b32_e32 v77, v139, v77, vcc
	v_cmp_lt_i32_e32 vcc, 0xf0, v8
	s_nop 1
	v_cndmask_b32_e32 v78, v139, v78, vcc
	v_cmp_lt_i32_e32 vcc, 0xf1, v8
	s_nop 1
	v_cndmask_b32_e32 v79, v139, v79, vcc
	v_cmp_lt_i32_e32 vcc, 0xf2, v8
	s_nop 1
	v_cndmask_b32_e32 v80, v139, v80, vcc
	v_cmp_lt_i32_e32 vcc, 0xf3, v8
	s_nop 1
	v_cndmask_b32_e32 v81, v139, v81, vcc
; DI float fast_exp2(float x) { return __builtin_amdgcn_exp2f(x); }
; DI void dsa_item(const Params& p, int b, int blk) {
;     ...
;     float inv[8];
;     #pragma unroll
;     for (int m = 0; m < 8; ++m) {
;       float mx = fmaxf(fmaxf(sc[0][m], sc[1][m]), fmaxf(sc[2][m], sc[3][m]));
;       mx = wave_max(mx);
;       float s = 0.f;
;       #pragma unroll
;       for (int rd = 0; rd < 4; ++rd) { sc[rd][m] = fast_exp2(sc[rd][m] - mx); s += sc[rd][m]; }
;       s = wave_sum(s);
;       inv[m] = 1.f / s;
;     }
.Lqk_nomask:
	v_max3_f32 v0, v18, v19, v20
	v_max3_f32 v0, v0, v21, v22
	v_max3_f32 v0, v0, v23, v24
	v_max3_f32 v0, v0, v25, v26
	v_max3_f32 v0, v0, v27, v28
	v_max3_f32 v0, v0, v29, v30
	v_max3_f32 v0, v0, v31, v32
	v_max3_f32 v0, v0, v33, v34
	v_max3_f32 v0, v0, v35, v36
	v_max3_f32 v0, v0, v37, v38
	v_max3_f32 v0, v0, v39, v40
	v_max3_f32 v0, v0, v41, v42
	v_max3_f32 v0, v0, v43, v44
	v_max3_f32 v0, v0, v45, v46
	v_max3_f32 v0, v0, v47, v48
	v_max3_f32 v0, v0, v49, v50
	v_max3_f32 v0, v0, v51, v52
	v_max3_f32 v0, v0, v53, v54
	v_max3_f32 v0, v0, v55, v56
	v_max3_f32 v0, v0, v57, v58
	v_max3_f32 v0, v0, v59, v60
	v_max3_f32 v0, v0, v61, v62
	v_max3_f32 v0, v0, v63, v64
	v_max3_f32 v0, v0, v65, v66
	v_max3_f32 v0, v0, v67, v68
	v_max3_f32 v0, v0, v69, v70
	v_max3_f32 v0, v0, v71, v72
	v_max3_f32 v0, v0, v73, v74
	v_max3_f32 v0, v0, v75, v76
	v_max3_f32 v0, v0, v77, v78
	v_max3_f32 v0, v0, v79, v80
	v_max_f32_e32 v0, v0, v81
	ds_bpermute_b32 v252, v9, v0
	s_waitcnt lgkmcnt(0)
	v_max_f32_e32 v0, v0, v252
	ds_bpermute_b32 v252, v10, v0
	s_waitcnt lgkmcnt(0)
	v_max_f32_e32 v0, v0, v252
	v_sub_f32_e32 v18, v18, v0
	v_sub_f32_e32 v19, v19, v0
	v_sub_f32_e32 v20, v20, v0
	v_sub_f32_e32 v21, v21, v0
	v_sub_f32_e32 v22, v22, v0
	v_sub_f32_e32 v23, v23, v0
	v_sub_f32_e32 v24, v24, v0
	v_sub_f32_e32 v25, v25, v0
	v_sub_f32_e32 v26, v26, v0
	v_sub_f32_e32 v27, v27, v0
	v_sub_f32_e32 v28, v28, v0
	v_sub_f32_e32 v29, v29, v0
	v_sub_f32_e32 v30, v30, v0
	v_sub_f32_e32 v31, v31, v0
	v_sub_f32_e32 v32, v32, v0
	v_sub_f32_e32 v33, v33, v0
	v_sub_f32_e32 v34, v34, v0
	v_sub_f32_e32 v35, v35, v0
	v_sub_f32_e32 v36, v36, v0
	v_sub_f32_e32 v37, v37, v0
	v_sub_f32_e32 v38, v38, v0
	v_sub_f32_e32 v39, v39, v0
	v_sub_f32_e32 v40, v40, v0
	v_sub_f32_e32 v41, v41, v0
	v_sub_f32_e32 v42, v42, v0
	v_sub_f32_e32 v43, v43, v0
	v_sub_f32_e32 v44, v44, v0
	v_sub_f32_e32 v45, v45, v0
	v_sub_f32_e32 v46, v46, v0
	v_sub_f32_e32 v47, v47, v0
	v_sub_f32_e32 v48, v48, v0
	v_sub_f32_e32 v49, v49, v0
	v_sub_f32_e32 v50, v50, v0
	v_sub_f32_e32 v51, v51, v0
	v_sub_f32_e32 v52, v52, v0
	v_sub_f32_e32 v53, v53, v0
	v_sub_f32_e32 v54, v54, v0
	v_sub_f32_e32 v55, v55, v0
	v_sub_f32_e32 v56, v56, v0
	v_sub_f32_e32 v57, v57, v0
	v_sub_f32_e32 v58, v58, v0
	v_sub_f32_e32 v59, v59, v0
	v_sub_f32_e32 v60, v60, v0
	v_sub_f32_e32 v61, v61, v0
	v_sub_f32_e32 v62, v62, v0
	v_sub_f32_e32 v63, v63, v0
	v_sub_f32_e32 v64, v64, v0
	v_sub_f32_e32 v65, v65, v0
	v_sub_f32_e32 v66, v66, v0
	v_sub_f32_e32 v67, v67, v0
	v_sub_f32_e32 v68, v68, v0
	v_sub_f32_e32 v69, v69, v0
	v_sub_f32_e32 v70, v70, v0
	v_sub_f32_e32 v71, v71, v0
	v_sub_f32_e32 v72, v72, v0
	v_sub_f32_e32 v73, v73, v0
	v_sub_f32_e32 v74, v74, v0
	v_sub_f32_e32 v75, v75, v0
	v_sub_f32_e32 v76, v76, v0
	v_sub_f32_e32 v77, v77, v0
	v_sub_f32_e32 v78, v78, v0
	v_sub_f32_e32 v79, v79, v0
	v_sub_f32_e32 v80, v80, v0
	v_sub_f32_e32 v81, v81, v0
	v_exp_f32_e32 v18, v18
	v_exp_f32_e32 v19, v19
	v_exp_f32_e32 v20, v20
	v_exp_f32_e32 v21, v21
	v_exp_f32_e32 v22, v22
	v_exp_f32_e32 v23, v23
	v_exp_f32_e32 v24, v24
	v_exp_f32_e32 v25, v25
	v_exp_f32_e32 v26, v26
	v_exp_f32_e32 v27, v27
	v_exp_f32_e32 v28, v28
	v_exp_f32_e32 v29, v29
	v_exp_f32_e32 v30, v30
	v_exp_f32_e32 v31, v31
	v_exp_f32_e32 v32, v32
	v_exp_f32_e32 v33, v33
	v_exp_f32_e32 v34, v34
	v_exp_f32_e32 v35, v35
	v_exp_f32_e32 v36, v36
	v_exp_f32_e32 v37, v37
	v_exp_f32_e32 v38, v38
	v_exp_f32_e32 v39, v39
	v_exp_f32_e32 v40, v40
	v_exp_f32_e32 v41, v41
	v_exp_f32_e32 v42, v42
	v_exp_f32_e32 v43, v43
	v_exp_f32_e32 v44, v44
	v_exp_f32_e32 v45, v45
	v_exp_f32_e32 v46, v46
	v_exp_f32_e32 v47, v47
	v_exp_f32_e32 v48, v48
	v_exp_f32_e32 v49, v49
	v_exp_f32_e32 v50, v50
	v_exp_f32_e32 v51, v51
	v_exp_f32_e32 v52, v52
	v_exp_f32_e32 v53, v53
	v_exp_f32_e32 v54, v54
	v_exp_f32_e32 v55, v55
	v_exp_f32_e32 v56, v56
	v_exp_f32_e32 v57, v57
	v_exp_f32_e32 v58, v58
	v_exp_f32_e32 v59, v59
	v_exp_f32_e32 v60, v60
	v_exp_f32_e32 v61, v61
	v_exp_f32_e32 v62, v62
	v_exp_f32_e32 v63, v63
	v_exp_f32_e32 v64, v64
	v_exp_f32_e32 v65, v65
	v_exp_f32_e32 v66, v66
	v_exp_f32_e32 v67, v67
	v_exp_f32_e32 v68, v68
	v_exp_f32_e32 v69, v69
	v_exp_f32_e32 v70, v70
	v_exp_f32_e32 v71, v71
	v_exp_f32_e32 v72, v72
	v_exp_f32_e32 v73, v73
	v_exp_f32_e32 v74, v74
	v_exp_f32_e32 v75, v75
	v_exp_f32_e32 v76, v76
	v_exp_f32_e32 v77, v77
	v_exp_f32_e32 v78, v78
	v_exp_f32_e32 v79, v79
	v_exp_f32_e32 v80, v80
	v_exp_f32_e32 v81, v81
	s_nop 0
	v_add_f32_e32 v253, v18, v19
	v_add_f32_e32 v253, v253, v20
	v_add_f32_e32 v253, v253, v21
	v_add_f32_e32 v253, v253, v22
	v_add_f32_e32 v253, v253, v23
	v_add_f32_e32 v253, v253, v24
	v_add_f32_e32 v253, v253, v25
	v_add_f32_e32 v253, v253, v26
	v_add_f32_e32 v253, v253, v27
	v_add_f32_e32 v253, v253, v28
	v_add_f32_e32 v253, v253, v29
	v_add_f32_e32 v253, v253, v30
	v_add_f32_e32 v253, v253, v31
	v_add_f32_e32 v253, v253, v32
	v_add_f32_e32 v253, v253, v33
	v_add_f32_e32 v253, v253, v34
	v_add_f32_e32 v253, v253, v35
	v_add_f32_e32 v253, v253, v36
	v_add_f32_e32 v253, v253, v37
	v_add_f32_e32 v253, v253, v38
	v_add_f32_e32 v253, v253, v39
	v_add_f32_e32 v253, v253, v40
	v_add_f32_e32 v253, v253, v41
	v_add_f32_e32 v253, v253, v42
	v_add_f32_e32 v253, v253, v43
	v_add_f32_e32 v253, v253, v44
	v_add_f32_e32 v253, v253, v45
	v_add_f32_e32 v253, v253, v46
	v_add_f32_e32 v253, v253, v47
	v_add_f32_e32 v253, v253, v48
	v_add_f32_e32 v253, v253, v49
	v_add_f32_e32 v253, v253, v50
	v_add_f32_e32 v253, v253, v51
	v_add_f32_e32 v253, v253, v52
	v_add_f32_e32 v253, v253, v53
	v_add_f32_e32 v253, v253, v54
	v_add_f32_e32 v253, v253, v55
	v_add_f32_e32 v253, v253, v56
	v_add_f32_e32 v253, v253, v57
	v_add_f32_e32 v253, v253, v58
	v_add_f32_e32 v253, v253, v59
	v_add_f32_e32 v253, v253, v60
	v_add_f32_e32 v253, v253, v61
	v_add_f32_e32 v253, v253, v62
	v_add_f32_e32 v253, v253, v63
	v_add_f32_e32 v253, v253, v64
	v_add_f32_e32 v253, v253, v65
	v_add_f32_e32 v253, v253, v66
	v_add_f32_e32 v253, v253, v67
	v_add_f32_e32 v253, v253, v68
	v_add_f32_e32 v253, v253, v69
	v_add_f32_e32 v253, v253, v70
	v_add_f32_e32 v253, v253, v71
	v_add_f32_e32 v253, v253, v72
	v_add_f32_e32 v253, v253, v73
	v_add_f32_e32 v253, v253, v74
	v_add_f32_e32 v253, v253, v75
	v_add_f32_e32 v253, v253, v76
	v_add_f32_e32 v253, v253, v77
	v_add_f32_e32 v253, v253, v78
	v_add_f32_e32 v253, v253, v79
	v_add_f32_e32 v253, v253, v80
	v_add_f32_e32 v253, v253, v81
	ds_bpermute_b32 v252, v9, v253
	s_waitcnt lgkmcnt(0)
; DI void dsa_item(const Params& p, int b, int blk) {
;     ...
;       inv[m] = 1.f / s;
;     }
;     #pragma unroll
;     for (int rd = 0; rd < 4; ++rd)
;       #pragma unroll
;       for (int m = 0; m < 8; ++m) Pb[m * PSTR + rd * 64 + lane] = f2bf(sc[rd][m] * inv[m]);
;     f32x4 oacc[8];
;     #pragma unroll
;     for (int c = 0; c < 8; ++c) oacc[c] = (f32x4){0.f, 0.f, 0.f, 0.f};
	v_add_f32_e32 v253, v253, v252
	ds_bpermute_b32 v252, v10, v253
	s_waitcnt lgkmcnt(0)
	v_add_f32_e32 v253, v253, v252
	v_div_scale_f32 v2, s[10:11], v253, v253, 1.0
	v_rcp_f32_e32 v3, v2
	s_nop 0
	v_fma_f32 v4, -v2, v3, 1.0
	v_fmac_f32_e32 v3, v4, v3
	v_div_scale_f32 v4, vcc, 1.0, v253, 1.0
	v_mul_f32_e32 v5, v4, v3
	v_fma_f32 v6, -v2, v5, v4
	v_fmac_f32_e32 v5, v6, v3
	v_fma_f32 v4, -v2, v5, v4
	s_nop 0
	v_div_fmas_f32 v4, v4, v3, v5
	v_div_fixup_f32 v4, v4, v253, 1.0
	v_mul_f32_e32 v18, v18, v4
	v_mul_f32_e32 v19, v19, v4
	v_mul_f32_e32 v20, v20, v4
	v_mul_f32_e32 v21, v21, v4
	v_mul_f32_e32 v22, v22, v4
	v_mul_f32_e32 v23, v23, v4
	v_mul_f32_e32 v24, v24, v4
	v_mul_f32_e32 v25, v25, v4
	v_mul_f32_e32 v26, v26, v4
	v_mul_f32_e32 v27, v27, v4
	v_mul_f32_e32 v28, v28, v4
	v_mul_f32_e32 v29, v29, v4
	v_mul_f32_e32 v30, v30, v4
	v_mul_f32_e32 v31, v31, v4
	v_mul_f32_e32 v32, v32, v4
	v_mul_f32_e32 v33, v33, v4
	v_mul_f32_e32 v34, v34, v4
	v_mul_f32_e32 v35, v35, v4
	v_mul_f32_e32 v36, v36, v4
	v_mul_f32_e32 v37, v37, v4
	v_mul_f32_e32 v38, v38, v4
	v_mul_f32_e32 v39, v39, v4
	v_mul_f32_e32 v40, v40, v4
	v_mul_f32_e32 v41, v41, v4
	v_mul_f32_e32 v42, v42, v4
	v_mul_f32_e32 v43, v43, v4
	v_mul_f32_e32 v44, v44, v4
	v_mul_f32_e32 v45, v45, v4
	v_mul_f32_e32 v46, v46, v4
	v_mul_f32_e32 v47, v47, v4
	v_mul_f32_e32 v48, v48, v4
	v_mul_f32_e32 v49, v49, v4
	v_mul_f32_e32 v50, v50, v4
	v_mul_f32_e32 v51, v51, v4
	v_mul_f32_e32 v52, v52, v4
	v_mul_f32_e32 v53, v53, v4
	v_mul_f32_e32 v54, v54, v4
	v_mul_f32_e32 v55, v55, v4
	v_mul_f32_e32 v56, v56, v4
	v_mul_f32_e32 v57, v57, v4
	v_mul_f32_e32 v58, v58, v4
	v_mul_f32_e32 v59, v59, v4
	v_mul_f32_e32 v60, v60, v4
	v_mul_f32_e32 v61, v61, v4
	v_mul_f32_e32 v62, v62, v4
	v_mul_f32_e32 v63, v63, v4
	v_mul_f32_e32 v64, v64, v4
	v_mul_f32_e32 v65, v65, v4
	v_mul_f32_e32 v66, v66, v4
	v_mul_f32_e32 v67, v67, v4
	v_mul_f32_e32 v68, v68, v4
	v_mul_f32_e32 v69, v69, v4
	v_mul_f32_e32 v70, v70, v4
	v_mul_f32_e32 v71, v71, v4
	v_mul_f32_e32 v72, v72, v4
	v_mul_f32_e32 v73, v73, v4
	v_mul_f32_e32 v74, v74, v4
	v_mul_f32_e32 v75, v75, v4
	v_mul_f32_e32 v76, v76, v4
	v_mul_f32_e32 v77, v77, v4
	v_mul_f32_e32 v78, v78, v4
	v_mul_f32_e32 v79, v79, v4
	v_mul_f32_e32 v80, v80, v4
	v_mul_f32_e32 v81, v81, v4
	v_cvt_pk_bf16_f32 v18, v18, v19
	v_cvt_pk_bf16_f32 v19, v20, v21
	v_cvt_pk_bf16_f32 v22, v22, v23
	v_cvt_pk_bf16_f32 v23, v24, v25
	v_cvt_pk_bf16_f32 v26, v26, v27
	v_cvt_pk_bf16_f32 v27, v28, v29
	v_cvt_pk_bf16_f32 v30, v30, v31
	v_cvt_pk_bf16_f32 v31, v32, v33
	v_cvt_pk_bf16_f32 v34, v34, v35
	v_cvt_pk_bf16_f32 v35, v36, v37
	v_cvt_pk_bf16_f32 v38, v38, v39
	v_cvt_pk_bf16_f32 v39, v40, v41
	v_cvt_pk_bf16_f32 v42, v42, v43
	v_cvt_pk_bf16_f32 v43, v44, v45
	v_cvt_pk_bf16_f32 v46, v46, v47
	v_cvt_pk_bf16_f32 v47, v48, v49
	v_cvt_pk_bf16_f32 v50, v50, v51
	v_cvt_pk_bf16_f32 v51, v52, v53
	v_cvt_pk_bf16_f32 v54, v54, v55
	v_cvt_pk_bf16_f32 v55, v56, v57
	v_cvt_pk_bf16_f32 v58, v58, v59
	v_cvt_pk_bf16_f32 v59, v60, v61
	v_cvt_pk_bf16_f32 v62, v62, v63
	v_cvt_pk_bf16_f32 v63, v64, v65
	v_cvt_pk_bf16_f32 v66, v66, v67
	v_cvt_pk_bf16_f32 v67, v68, v69
	v_cvt_pk_bf16_f32 v70, v70, v71
	v_cvt_pk_bf16_f32 v71, v72, v73
	v_cvt_pk_bf16_f32 v74, v74, v75
	v_cvt_pk_bf16_f32 v75, v76, v77
	v_cvt_pk_bf16_f32 v78, v78, v79
	v_cvt_pk_bf16_f32 v79, v80, v81
	s_mov_b32 exec_lo, 0x00ff00ff
	s_mov_b32 exec_hi, 0x00ff00ff
	ds_write_b64 v138, v[18:19]
	ds_write_b64 v138, v[22:23] offset:32
	ds_write_b64 v138, v[26:27] offset:64
	ds_write_b64 v138, v[30:31] offset:96
	ds_write_b64 v138, v[34:35] offset:128
	ds_write_b64 v138, v[38:39] offset:160
	ds_write_b64 v138, v[42:43] offset:192
	ds_write_b64 v138, v[46:47] offset:224
	ds_write_b64 v138, v[50:51] offset:256
	ds_write_b64 v138, v[54:55] offset:288
	ds_write_b64 v138, v[58:59] offset:320
	ds_write_b64 v138, v[62:63] offset:352
	ds_write_b64 v138, v[66:67] offset:384
	ds_write_b64 v138, v[70:71] offset:416
	ds_write_b64 v138, v[74:75] offset:448
	ds_write_b64 v138, v[78:79] offset:480
	s_mov_b64 exec, -1
	v_lshlrev_b64 v[66:67], 9, v[152:153]
	v_mov_b32_e32 v68, v161
	v_mov_b32_e32 v50, 0
	v_mov_b32_e32 v51, 0
	v_mov_b32_e32 v52, 0
	v_mov_b32_e32 v53, 0
	v_mov_b32_e32 v38, 0
	v_mov_b32_e32 v39, 0
	v_mov_b32_e32 v40, 0
	v_mov_b32_e32 v41, 0
	v_mov_b32_e32 v30, 0
	v_mov_b32_e32 v31, 0
	v_mov_b32_e32 v32, 0
	v_mov_b32_e32 v33, 0
	v_mov_b32_e32 v18, 0
	v_mov_b32_e32 v19, 0
	v_mov_b32_e32 v20, 0
	v_mov_b32_e32 v21, 0
	v_mov_b32_e32 v42, 0
	v_mov_b32_e32 v43, 0
	v_mov_b32_e32 v44, 0
	v_mov_b32_e32 v45, 0
	v_mov_b32_e32 v26, 0
	v_mov_b32_e32 v27, 0
	v_mov_b32_e32 v28, 0
	v_mov_b32_e32 v29, 0
	v_mov_b32_e32 v14, 0
	v_mov_b32_e32 v15, 0
	v_mov_b32_e32 v16, 0
	v_mov_b32_e32 v17, 0
	v_mov_b32_e32 v6, 0
	v_mov_b32_e32 v7, 0
	v_mov_b32_e32 v8, 0
	v_mov_b32_e32 v9, 0
	v_and_b32_e32 v253, 15, v187
	v_lshlrev_b32_e32 v253, 4, v253
	ds_read_b128 v[248:251], v242 offset:128
	s_waitcnt lgkmcnt(0)
; DI void dsa_item(const Params& p, int b, int blk) {
;     ...
;     #pragma unroll 1
;     for (int kc = 0; kc < 8; ++kc) {
;       #pragma unroll
;       for (int j = 0; j < 8; ++j) {
;         const unsigned row = 8 * g16 + j;
;         *(u32x4*)(Vc + 256u * row + 16u * ((unsigned)n16 ^ (((row & 3) << 2) | ((row >> 2) & 3)))) = vr[j];
;       }
;       if (kc < 7) {
;         const u32x4 si = *(const u32x4*)(sel + qq * 256 + (kc + 1) * 32 + 8 * g16);
;         #pragma unroll
;         for (int j = 0; j < 8; ++j) {
;           const int ks = (kc + 1) * 32 + 8 * g16 + j;
;           const int idx = ks < cnt ? (int)((si[j >> 1] >> (16 * (j & 1))) & 0xffffu) : 0;
;           vr[j] = ldg<u32x4>(Av + (rowbase + idx) * 128 + n16 * 8);
;         }
;       }
;       const bf16x8 pa = *(const bf16x8*)(Pb + arow * PSTR + kc * 32 + g16 * 8);
;       u32x2 t0[8], t1[8];
;       asm volatile(
;           "s_waitcnt lgkmcnt(0)\n\t"
;           "ds_read_b64_tr_b16 %0, %16\n\tds_read_b64_tr_b16 %1, %17\n\tds_read_b64_tr_b16 %2, %18\n\tds_read_b64_tr_b16 %3, %19\n\t"
;           "ds_read_b64_tr_b16 %4, %20\n\tds_read_b64_tr_b16 %5, %21\n\tds_read_b64_tr_b16 %6, %22\n\tds_read_b64_tr_b16 %7, %23\n\t"
;           "ds_read_b64_tr_b16 %8, %24\n\tds_read_b64_tr_b16 %9, %25\n\tds_read_b64_tr_b16 %10, %26\n\tds_read_b64_tr_b16 %11, %27\n\t"
;           "ds_read_b64_tr_b16 %12, %28\n\tds_read_b64_tr_b16 %13, %29\n\tds_read_b64_tr_b16 %14, %30\n\tds_read_b64_tr_b16 %15, %31\n\t"
;           "s_waitcnt lgkmcnt(0)"
;           : "=&v"(t0[0]), "=&v"(t1[0]), "=&v"(t0[1]), "=&v"(t1[1]), "=&v"(t0[2]), "=&v"(t1[2]), "=&v"(t0[3]), "=&v"(t1[3]),
;             "=&v"(t0[4]), "=&v"(t1[4]), "=&v"(t0[5]), "=&v"(t1[5]), "=&v"(t0[6]), "=&v"(t1[6]), "=&v"(t0[7]), "=&v"(t1[7])
;           : "v"(lds_base + taddr[0][0]), "v"(lds_base + taddr[0][1]), "v"(lds_base + taddr[1][0]), "v"(lds_base + taddr[1][1]),
;             "v"(lds_base + taddr[2][0]), "v"(lds_base + taddr[2][1]), "v"(lds_base + taddr[3][0]), "v"(lds_base + taddr[3][1]),
;             "v"(lds_base + taddr[4][0]), "v"(lds_base + taddr[4][1]), "v"(lds_base + taddr[5][0]), "v"(lds_base + taddr[5][1]),
;             "v"(lds_base + taddr[6][0]), "v"(lds_base + taddr[6][1]), "v"(lds_base + taddr[7][0]), "v"(lds_base + taddr[7][1])
;           : "memory");
;       #pragma unroll
;       for (int c = 0; c < 8; ++c) {
	v_add_u32_e32 v243, 0xffffffc0, v206
	v_cmp_lt_i32_e32 vcc, v156, v243
	s_nop 1
	v_cndmask_b32_sdwa v240, v1, v248, vcc dst_sel:DWORD dst_unused:UNUSED_PAD src0_sel:DWORD src1_sel:WORD_0
	v_cmp_lt_i32_e32 vcc, v192, v243
	v_lshl_add_u32 v244, v240, 8, v253
	global_load_dwordx4 v[2:5], v244, s[12:13]
	v_cndmask_b32_sdwa v240, v1, v248, vcc dst_sel:DWORD dst_unused:UNUSED_PAD src0_sel:DWORD src1_sel:WORD_1
	v_cmp_lt_i32_e32 vcc, v193, v243
	v_lshl_add_u32 v245, v240, 8, v253
	global_load_dwordx4 v[10:13], v245, s[12:13]
	v_cndmask_b32_sdwa v240, v1, v249, vcc dst_sel:DWORD dst_unused:UNUSED_PAD src0_sel:DWORD src1_sel:WORD_0
	v_cmp_lt_i32_e32 vcc, v194, v243
	v_lshl_add_u32 v246, v240, 8, v253
	global_load_dwordx4 v[22:25], v246, s[12:13]
	v_cndmask_b32_sdwa v240, v1, v249, vcc dst_sel:DWORD dst_unused:UNUSED_PAD src0_sel:DWORD src1_sel:WORD_1
	v_cmp_lt_i32_e32 vcc, v157, v243
	v_lshl_add_u32 v247, v240, 8, v253
	global_load_dwordx4 v[34:37], v247, s[12:13]
	v_cndmask_b32_sdwa v240, v1, v250, vcc dst_sel:DWORD dst_unused:UNUSED_PAD src0_sel:DWORD src1_sel:WORD_0
	v_cmp_lt_i32_e32 vcc, v195, v243
	v_lshl_add_u32 v244, v240, 8, v253
	global_load_dwordx4 v[46:49], v244, s[12:13]
	v_cndmask_b32_sdwa v240, v1, v250, vcc dst_sel:DWORD dst_unused:UNUSED_PAD src0_sel:DWORD src1_sel:WORD_1
	v_cmp_lt_i32_e32 vcc, v196, v243
	v_lshl_add_u32 v245, v240, 8, v253
	global_load_dwordx4 v[54:57], v245, s[12:13]
	v_cndmask_b32_sdwa v240, v1, v251, vcc dst_sel:DWORD dst_unused:UNUSED_PAD src0_sel:DWORD src1_sel:WORD_0
	v_cmp_lt_i32_e32 vcc, v197, v243
	v_lshl_add_u32 v246, v240, 8, v253
	global_load_dwordx4 v[58:61], v246, s[12:13]
	v_cndmask_b32_sdwa v240, v1, v251, vcc dst_sel:DWORD dst_unused:UNUSED_PAD src0_sel:DWORD src1_sel:WORD_1
	v_lshl_add_u32 v247, v240, 8, v253
	global_load_dwordx4 v[62:65], v247, s[12:13]
	s_waitcnt vmcnt(16)
	ds_write_b128 v198, v[208:211]
	ds_write_b128 v199, v[212:215]
	ds_write_b128 v200, v[216:219]
	ds_write_b128 v201, v[220:223]
	ds_write_b128 v202, v[224:227]
	ds_write_b128 v203, v[228:231]
	ds_write_b128 v204, v[232:235]
	ds_write_b128 v205, v[236:239]
	ds_read_b128 v[248:251], v242 offset:192
	s_waitcnt lgkmcnt(0)
	v_add_u32_e32 v243, 0xffffffa0, v206
	v_cmp_lt_i32_e32 vcc, v156, v243
	s_nop 1
	v_cndmask_b32_sdwa v240, v1, v248, vcc dst_sel:DWORD dst_unused:UNUSED_PAD src0_sel:DWORD src1_sel:WORD_0
	v_cmp_lt_i32_e32 vcc, v192, v243
	v_lshl_add_u32 v244, v240, 8, v253
	global_load_dwordx4 v[208:211], v244, s[12:13]
	v_cndmask_b32_sdwa v240, v1, v248, vcc dst_sel:DWORD dst_unused:UNUSED_PAD src0_sel:DWORD src1_sel:WORD_1
	v_cmp_lt_i32_e32 vcc, v193, v243
	v_lshl_add_u32 v245, v240, 8, v253
	global_load_dwordx4 v[212:215], v245, s[12:13]
	v_cndmask_b32_sdwa v240, v1, v249, vcc dst_sel:DWORD dst_unused:UNUSED_PAD src0_sel:DWORD src1_sel:WORD_0
	v_cmp_lt_i32_e32 vcc, v194, v243
	v_lshl_add_u32 v246, v240, 8, v253
	global_load_dwordx4 v[216:219], v246, s[12:13]
	v_cndmask_b32_sdwa v240, v1, v249, vcc dst_sel:DWORD dst_unused:UNUSED_PAD src0_sel:DWORD src1_sel:WORD_1
	v_cmp_lt_i32_e32 vcc, v157, v243
	v_lshl_add_u32 v247, v240, 8, v253
	global_load_dwordx4 v[220:223], v247, s[12:13]
	v_cndmask_b32_sdwa v240, v1, v250, vcc dst_sel:DWORD dst_unused:UNUSED_PAD src0_sel:DWORD src1_sel:WORD_0
	v_cmp_lt_i32_e32 vcc, v195, v243
	v_lshl_add_u32 v244, v240, 8, v253
	global_load_dwordx4 v[224:227], v244, s[12:13]
	v_cndmask_b32_sdwa v240, v1, v250, vcc dst_sel:DWORD dst_unused:UNUSED_PAD src0_sel:DWORD src1_sel:WORD_1
	v_cmp_lt_i32_e32 vcc, v196, v243
	v_lshl_add_u32 v245, v240, 8, v253
	global_load_dwordx4 v[228:231], v245, s[12:13]
	v_cndmask_b32_sdwa v240, v1, v251, vcc dst_sel:DWORD dst_unused:UNUSED_PAD src0_sel:DWORD src1_sel:WORD_0
	v_cmp_lt_i32_e32 vcc, v197, v243
	v_lshl_add_u32 v246, v240, 8, v253
	global_load_dwordx4 v[232:235], v246, s[12:13]
	v_cndmask_b32_sdwa v240, v1, v251, vcc dst_sel:DWORD dst_unused:UNUSED_PAD src0_sel:DWORD src1_sel:WORD_1
	v_lshl_add_u32 v247, v240, 8, v253
	global_load_dwordx4 v[236:239], v247, s[12:13]
	ds_read_b128 v[70:73], v68
	s_waitcnt lgkmcnt(0)
	ds_read_b64_tr_b16 v[102:103], v162
	ds_read_b64_tr_b16 v[104:105], v163
	ds_read_b64_tr_b16 v[98:99], v164
	ds_read_b64_tr_b16 v[100:101], v165
	ds_read_b64_tr_b16 v[94:95], v166
	ds_read_b64_tr_b16 v[96:97], v167
	ds_read_b64_tr_b16 v[90:91], v168
	ds_read_b64_tr_b16 v[92:93], v169
	ds_read_b64_tr_b16 v[86:87], v170
	ds_read_b64_tr_b16 v[88:89], v171
	ds_read_b64_tr_b16 v[82:83], v172
	ds_read_b64_tr_b16 v[84:85], v173
	ds_read_b64_tr_b16 v[78:79], v174
	ds_read_b64_tr_b16 v[80:81], v175
	ds_read_b64_tr_b16 v[74:75], v176
	ds_read_b64_tr_b16 v[76:77], v177
	s_waitcnt lgkmcnt(0)
	v_mfma_f32_16x16x32_bf16 v[50:53], v[70:73], v[102:105], v[50:53]
	v_mfma_f32_16x16x32_bf16 v[38:41], v[70:73], v[98:101], v[38:41]
	v_mfma_f32_16x16x32_bf16 v[30:33], v[70:73], v[94:97], v[30:33]
	v_mfma_f32_16x16x32_bf16 v[18:21], v[70:73], v[90:93], v[18:21]
	v_mfma_f32_16x16x32_bf16 v[42:45], v[70:73], v[86:89], v[42:45]
	v_mfma_f32_16x16x32_bf16 v[26:29], v[70:73], v[82:85], v[26:29]
	v_mfma_f32_16x16x32_bf16 v[14:17], v[70:73], v[78:81], v[14:17]
	v_mfma_f32_16x16x32_bf16 v[6:9], v[70:73], v[74:77], v[6:9]
	s_waitcnt vmcnt(16)
	ds_write_b128 v198, v[106:109]
	ds_write_b128 v199, v[110:113]
	ds_write_b128 v200, v[114:117]
	ds_write_b128 v201, v[118:121]
	ds_write_b128 v202, v[122:125]
	ds_write_b128 v203, v[126:129]
	ds_write_b128 v204, v[130:133]
	ds_write_b128 v205, v[134:137]
	ds_read_b128 v[248:251], v242 offset:256
	s_waitcnt lgkmcnt(0)
; DI void dsa_item(const Params& p, int b, int blk) {
;     ...
;     #pragma unroll 1
;     for (int kc = 0; kc < 8; ++kc) {
;       #pragma unroll
;       for (int j = 0; j < 8; ++j) {
;         const unsigned row = 8 * g16 + j;
;         *(u32x4*)(Vc + 256u * row + 16u * ((unsigned)n16 ^ (((row & 3) << 2) | ((row >> 2) & 3)))) = vr[j];
;       }
;       if (kc < 7) {
;         const u32x4 si = *(const u32x4*)(sel + qq * 256 + (kc + 1) * 32 + 8 * g16);
;         #pragma unroll
;         for (int j = 0; j < 8; ++j) {
;           const int ks = (kc + 1) * 32 + 8 * g16 + j;
;           const int idx = ks < cnt ? (int)((si[j >> 1] >> (16 * (j & 1))) & 0xffffu) : 0;
;           vr[j] = ldg<u32x4>(Av + (rowbase + idx) * 128 + n16 * 8);
;         }
;       }
;       const bf16x8 pa = *(const bf16x8*)(Pb + arow * PSTR + kc * 32 + g16 * 8);
;       u32x2 t0[8], t1[8];
;       asm volatile(
;           "s_waitcnt lgkmcnt(0)\n\t"
;           "ds_read_b64_tr_b16 %0, %16\n\tds_read_b64_tr_b16 %1, %17\n\tds_read_b64_tr_b16 %2, %18\n\tds_read_b64_tr_b16 %3, %19\n\t"
;           "ds_read_b64_tr_b16 %4, %20\n\tds_read_b64_tr_b16 %5, %21\n\tds_read_b64_tr_b16 %6, %22\n\tds_read_b64_tr_b16 %7, %23\n\t"
;           "ds_read_b64_tr_b16 %8, %24\n\tds_read_b64_tr_b16 %9, %25\n\tds_read_b64_tr_b16 %10, %26\n\tds_read_b64_tr_b16 %11, %27\n\t"
;           "ds_read_b64_tr_b16 %12, %28\n\tds_read_b64_tr_b16 %13, %29\n\tds_read_b64_tr_b16 %14, %30\n\tds_read_b64_tr_b16 %15, %31\n\t"
;           "s_waitcnt lgkmcnt(0)"
;           : "=&v"(t0[0]), "=&v"(t1[0]), "=&v"(t0[1]), "=&v"(t1[1]), "=&v"(t0[2]), "=&v"(t1[2]), "=&v"(t0[3]), "=&v"(t1[3]),
;             "=&v"(t0[4]), "=&v"(t1[4]), "=&v"(t0[5]), "=&v"(t1[5]), "=&v"(t0[6]), "=&v"(t1[6]), "=&v"(t0[7]), "=&v"(t1[7])
;           : "v"(lds_base + taddr[0][0]), "v"(lds_base + taddr[0][1]), "v"(lds_base + taddr[1][0]), "v"(lds_base + taddr[1][1]),
;             "v"(lds_base + taddr[2][0]), "v"(lds_base + taddr[2][1]), "v"(lds_base + taddr[3][0]), "v"(lds_base + taddr[3][1]),
;             "v"(lds_base + taddr[4][0]), "v"(lds_base + taddr[4][1]), "v"(lds_base + taddr[5][0]), "v"(lds_base + taddr[5][1]),
;             "v"(lds_base + taddr[6][0]), "v"(lds_base + taddr[6][1]), "v"(lds_base + taddr[7][0]), "v"(lds_base + taddr[7][1])
;           : "memory");
;       #pragma unroll
;       for (int c = 0; c < 8; ++c) {
	v_add_u32_e32 v243, 0xffffff80, v206
	v_cmp_lt_i32_e32 vcc, v156, v243
	s_nop 1
	v_cndmask_b32_sdwa v240, v1, v248, vcc dst_sel:DWORD dst_unused:UNUSED_PAD src0_sel:DWORD src1_sel:WORD_0
	v_cmp_lt_i32_e32 vcc, v192, v243
	v_lshl_add_u32 v244, v240, 8, v253
	global_load_dwordx4 v[106:109], v244, s[12:13]
	v_cndmask_b32_sdwa v240, v1, v248, vcc dst_sel:DWORD dst_unused:UNUSED_PAD src0_sel:DWORD src1_sel:WORD_1
	v_cmp_lt_i32_e32 vcc, v193, v243
	v_lshl_add_u32 v245, v240, 8, v253
	global_load_dwordx4 v[110:113], v245, s[12:13]
	v_cndmask_b32_sdwa v240, v1, v249, vcc dst_sel:DWORD dst_unused:UNUSED_PAD src0_sel:DWORD src1_sel:WORD_0
	v_cmp_lt_i32_e32 vcc, v194, v243
	v_lshl_add_u32 v246, v240, 8, v253
	global_load_dwordx4 v[114:117], v246, s[12:13]
	v_cndmask_b32_sdwa v240, v1, v249, vcc dst_sel:DWORD dst_unused:UNUSED_PAD src0_sel:DWORD src1_sel:WORD_1
	v_cmp_lt_i32_e32 vcc, v157, v243
	v_lshl_add_u32 v247, v240, 8, v253
	global_load_dwordx4 v[118:121], v247, s[12:13]
	v_cndmask_b32_sdwa v240, v1, v250, vcc dst_sel:DWORD dst_unused:UNUSED_PAD src0_sel:DWORD src1_sel:WORD_0
	v_cmp_lt_i32_e32 vcc, v195, v243
	v_lshl_add_u32 v244, v240, 8, v253
	global_load_dwordx4 v[122:125], v244, s[12:13]
	v_cndmask_b32_sdwa v240, v1, v250, vcc dst_sel:DWORD dst_unused:UNUSED_PAD src0_sel:DWORD src1_sel:WORD_1
	v_cmp_lt_i32_e32 vcc, v196, v243
	v_lshl_add_u32 v245, v240, 8, v253
	global_load_dwordx4 v[126:129], v245, s[12:13]
	v_cndmask_b32_sdwa v240, v1, v251, vcc dst_sel:DWORD dst_unused:UNUSED_PAD src0_sel:DWORD src1_sel:WORD_0
	v_cmp_lt_i32_e32 vcc, v197, v243
	v_lshl_add_u32 v246, v240, 8, v253
	global_load_dwordx4 v[130:133], v246, s[12:13]
	v_cndmask_b32_sdwa v240, v1, v251, vcc dst_sel:DWORD dst_unused:UNUSED_PAD src0_sel:DWORD src1_sel:WORD_1
	v_lshl_add_u32 v247, v240, 8, v253
	global_load_dwordx4 v[134:137], v247, s[12:13]
	ds_read_b128 v[70:73], v68 offset:64
	s_waitcnt lgkmcnt(0)
	ds_read_b64_tr_b16 v[102:103], v162
	ds_read_b64_tr_b16 v[104:105], v163
	ds_read_b64_tr_b16 v[98:99], v164
	ds_read_b64_tr_b16 v[100:101], v165
	ds_read_b64_tr_b16 v[94:95], v166
	ds_read_b64_tr_b16 v[96:97], v167
	ds_read_b64_tr_b16 v[90:91], v168
	ds_read_b64_tr_b16 v[92:93], v169
	ds_read_b64_tr_b16 v[86:87], v170
	ds_read_b64_tr_b16 v[88:89], v171
	ds_read_b64_tr_b16 v[82:83], v172
	ds_read_b64_tr_b16 v[84:85], v173
	ds_read_b64_tr_b16 v[78:79], v174
	ds_read_b64_tr_b16 v[80:81], v175
	ds_read_b64_tr_b16 v[74:75], v176
	ds_read_b64_tr_b16 v[76:77], v177
	s_waitcnt lgkmcnt(0)
	v_mfma_f32_16x16x32_bf16 v[50:53], v[70:73], v[102:105], v[50:53]
	v_mfma_f32_16x16x32_bf16 v[38:41], v[70:73], v[98:101], v[38:41]
	v_mfma_f32_16x16x32_bf16 v[30:33], v[70:73], v[94:97], v[30:33]
	v_mfma_f32_16x16x32_bf16 v[18:21], v[70:73], v[90:93], v[18:21]
	v_mfma_f32_16x16x32_bf16 v[42:45], v[70:73], v[86:89], v[42:45]
	v_mfma_f32_16x16x32_bf16 v[26:29], v[70:73], v[82:85], v[26:29]
	v_mfma_f32_16x16x32_bf16 v[14:17], v[70:73], v[78:81], v[14:17]
	v_mfma_f32_16x16x32_bf16 v[6:9], v[70:73], v[74:77], v[6:9]
	s_waitcnt vmcnt(16)
	ds_write_b128 v198, v[2:5]
	ds_write_b128 v199, v[10:13]
	ds_write_b128 v200, v[22:25]
	ds_write_b128 v201, v[34:37]
	ds_write_b128 v202, v[46:49]
	ds_write_b128 v203, v[54:57]
	ds_write_b128 v204, v[58:61]
	ds_write_b128 v205, v[62:65]
	ds_read_b128 v[248:251], v242 offset:320
	s_waitcnt lgkmcnt(0)
	v_add_u32_e32 v243, 0xffffff60, v206
	v_cmp_lt_i32_e32 vcc, v156, v243
	s_nop 1
	v_cndmask_b32_sdwa v240, v1, v248, vcc dst_sel:DWORD dst_unused:UNUSED_PAD src0_sel:DWORD src1_sel:WORD_0
	v_cmp_lt_i32_e32 vcc, v192, v243
	v_lshl_add_u32 v244, v240, 8, v253
	global_load_dwordx4 v[2:5], v244, s[12:13]
	v_cndmask_b32_sdwa v240, v1, v248, vcc dst_sel:DWORD dst_unused:UNUSED_PAD src0_sel:DWORD src1_sel:WORD_1
	v_cmp_lt_i32_e32 vcc, v193, v243
	v_lshl_add_u32 v245, v240, 8, v253
	global_load_dwordx4 v[10:13], v245, s[12:13]
	v_cndmask_b32_sdwa v240, v1, v249, vcc dst_sel:DWORD dst_unused:UNUSED_PAD src0_sel:DWORD src1_sel:WORD_0
	v_cmp_lt_i32_e32 vcc, v194, v243
	v_lshl_add_u32 v246, v240, 8, v253
	global_load_dwordx4 v[22:25], v246, s[12:13]
	v_cndmask_b32_sdwa v240, v1, v249, vcc dst_sel:DWORD dst_unused:UNUSED_PAD src0_sel:DWORD src1_sel:WORD_1
	v_cmp_lt_i32_e32 vcc, v157, v243
	v_lshl_add_u32 v247, v240, 8, v253
	global_load_dwordx4 v[34:37], v247, s[12:13]
	v_cndmask_b32_sdwa v240, v1, v250, vcc dst_sel:DWORD dst_unused:UNUSED_PAD src0_sel:DWORD src1_sel:WORD_0
	v_cmp_lt_i32_e32 vcc, v195, v243
	v_lshl_add_u32 v244, v240, 8, v253
	global_load_dwordx4 v[46:49], v244, s[12:13]
	v_cndmask_b32_sdwa v240, v1, v250, vcc dst_sel:DWORD dst_unused:UNUSED_PAD src0_sel:DWORD src1_sel:WORD_1
	v_cmp_lt_i32_e32 vcc, v196, v243
	v_lshl_add_u32 v245, v240, 8, v253
	global_load_dwordx4 v[54:57], v245, s[12:13]
	v_cndmask_b32_sdwa v240, v1, v251, vcc dst_sel:DWORD dst_unused:UNUSED_PAD src0_sel:DWORD src1_sel:WORD_0
	v_cmp_lt_i32_e32 vcc, v197, v243
	v_lshl_add_u32 v246, v240, 8, v253
	global_load_dwordx4 v[58:61], v246, s[12:13]
	v_cndmask_b32_sdwa v240, v1, v251, vcc dst_sel:DWORD dst_unused:UNUSED_PAD src0_sel:DWORD src1_sel:WORD_1
	v_lshl_add_u32 v247, v240, 8, v253
	global_load_dwordx4 v[62:65], v247, s[12:13]
	ds_read_b128 v[70:73], v68 offset:128
	s_waitcnt lgkmcnt(0)
	ds_read_b64_tr_b16 v[102:103], v162
	ds_read_b64_tr_b16 v[104:105], v163
	ds_read_b64_tr_b16 v[98:99], v164
	ds_read_b64_tr_b16 v[100:101], v165
	ds_read_b64_tr_b16 v[94:95], v166
	ds_read_b64_tr_b16 v[96:97], v167
	ds_read_b64_tr_b16 v[90:91], v168
	ds_read_b64_tr_b16 v[92:93], v169
	ds_read_b64_tr_b16 v[86:87], v170
	ds_read_b64_tr_b16 v[88:89], v171
	ds_read_b64_tr_b16 v[82:83], v172
	ds_read_b64_tr_b16 v[84:85], v173
	ds_read_b64_tr_b16 v[78:79], v174
	ds_read_b64_tr_b16 v[80:81], v175
	ds_read_b64_tr_b16 v[74:75], v176
	ds_read_b64_tr_b16 v[76:77], v177
	s_waitcnt lgkmcnt(0)
; DI void dsa_item(const Params& p, int b, int blk) {
;     ...
;     #pragma unroll 1
;     for (int kc = 0; kc < 8; ++kc) {
;       #pragma unroll
;       for (int j = 0; j < 8; ++j) {
;         const unsigned row = 8 * g16 + j;
;         *(u32x4*)(Vc + 256u * row + 16u * ((unsigned)n16 ^ (((row & 3) << 2) | ((row >> 2) & 3)))) = vr[j];
;       }
;       if (kc < 7) {
;         const u32x4 si = *(const u32x4*)(sel + qq * 256 + (kc + 1) * 32 + 8 * g16);
;         #pragma unroll
;         for (int j = 0; j < 8; ++j) {
;           const int ks = (kc + 1) * 32 + 8 * g16 + j;
;           const int idx = ks < cnt ? (int)((si[j >> 1] >> (16 * (j & 1))) & 0xffffu) : 0;
;           vr[j] = ldg<u32x4>(Av + (rowbase + idx) * 128 + n16 * 8);
;         }
;       }
;       const bf16x8 pa = *(const bf16x8*)(Pb + arow * PSTR + kc * 32 + g16 * 8);
;       u32x2 t0[8], t1[8];
;       asm volatile(
;           "s_waitcnt lgkmcnt(0)\n\t"
;           "ds_read_b64_tr_b16 %0, %16\n\tds_read_b64_tr_b16 %1, %17\n\tds_read_b64_tr_b16 %2, %18\n\tds_read_b64_tr_b16 %3, %19\n\t"
;           "ds_read_b64_tr_b16 %4, %20\n\tds_read_b64_tr_b16 %5, %21\n\tds_read_b64_tr_b16 %6, %22\n\tds_read_b64_tr_b16 %7, %23\n\t"
;           "ds_read_b64_tr_b16 %8, %24\n\tds_read_b64_tr_b16 %9, %25\n\tds_read_b64_tr_b16 %10, %26\n\tds_read_b64_tr_b16 %11, %27\n\t"
;           "ds_read_b64_tr_b16 %12, %28\n\tds_read_b64_tr_b16 %13, %29\n\tds_read_b64_tr_b16 %14, %30\n\tds_read_b64_tr_b16 %15, %31\n\t"
;           "s_waitcnt lgkmcnt(0)"
;           : "=&v"(t0[0]), "=&v"(t1[0]), "=&v"(t0[1]), "=&v"(t1[1]), "=&v"(t0[2]), "=&v"(t1[2]), "=&v"(t0[3]), "=&v"(t1[3]),
;             "=&v"(t0[4]), "=&v"(t1[4]), "=&v"(t0[5]), "=&v"(t1[5]), "=&v"(t0[6]), "=&v"(t1[6]), "=&v"(t0[7]), "=&v"(t1[7])
;           : "v"(lds_base + taddr[0][0]), "v"(lds_base + taddr[0][1]), "v"(lds_base + taddr[1][0]), "v"(lds_base + taddr[1][1]),
;             "v"(lds_base + taddr[2][0]), "v"(lds_base + taddr[2][1]), "v"(lds_base + taddr[3][0]), "v"(lds_base + taddr[3][1]),
;             "v"(lds_base + taddr[4][0]), "v"(lds_base + taddr[4][1]), "v"(lds_base + taddr[5][0]), "v"(lds_base + taddr[5][1]),
;             "v"(lds_base + taddr[6][0]), "v"(lds_base + taddr[6][1]), "v"(lds_base + taddr[7][0]), "v"(lds_base + taddr[7][1])
;           : "memory");
;       #pragma unroll
;       for (int c = 0; c < 8; ++c) {
	v_mfma_f32_16x16x32_bf16 v[50:53], v[70:73], v[102:105], v[50:53]
	v_mfma_f32_16x16x32_bf16 v[38:41], v[70:73], v[98:101], v[38:41]
	v_mfma_f32_16x16x32_bf16 v[30:33], v[70:73], v[94:97], v[30:33]
	v_mfma_f32_16x16x32_bf16 v[18:21], v[70:73], v[90:93], v[18:21]
	v_mfma_f32_16x16x32_bf16 v[42:45], v[70:73], v[86:89], v[42:45]
	v_mfma_f32_16x16x32_bf16 v[26:29], v[70:73], v[82:85], v[26:29]
	v_mfma_f32_16x16x32_bf16 v[14:17], v[70:73], v[78:81], v[14:17]
	v_mfma_f32_16x16x32_bf16 v[6:9], v[70:73], v[74:77], v[6:9]
	s_waitcnt vmcnt(16)
	ds_write_b128 v198, v[208:211]
	ds_write_b128 v199, v[212:215]
	ds_write_b128 v200, v[216:219]
	ds_write_b128 v201, v[220:223]
	ds_write_b128 v202, v[224:227]
	ds_write_b128 v203, v[228:231]
	ds_write_b128 v204, v[232:235]
	ds_write_b128 v205, v[236:239]
	ds_read_b128 v[248:251], v242 offset:384
	s_waitcnt lgkmcnt(0)
	v_add_u32_e32 v243, 0xffffff40, v206
	v_cmp_lt_i32_e32 vcc, v156, v243
	s_nop 1
	v_cndmask_b32_sdwa v240, v1, v248, vcc dst_sel:DWORD dst_unused:UNUSED_PAD src0_sel:DWORD src1_sel:WORD_0
	v_cmp_lt_i32_e32 vcc, v192, v243
	v_lshl_add_u32 v244, v240, 8, v253
	global_load_dwordx4 v[208:211], v244, s[12:13]
	v_cndmask_b32_sdwa v240, v1, v248, vcc dst_sel:DWORD dst_unused:UNUSED_PAD src0_sel:DWORD src1_sel:WORD_1
	v_cmp_lt_i32_e32 vcc, v193, v243
	v_lshl_add_u32 v245, v240, 8, v253
	global_load_dwordx4 v[212:215], v245, s[12:13]
	v_cndmask_b32_sdwa v240, v1, v249, vcc dst_sel:DWORD dst_unused:UNUSED_PAD src0_sel:DWORD src1_sel:WORD_0
	v_cmp_lt_i32_e32 vcc, v194, v243
	v_lshl_add_u32 v246, v240, 8, v253
	global_load_dwordx4 v[216:219], v246, s[12:13]
	v_cndmask_b32_sdwa v240, v1, v249, vcc dst_sel:DWORD dst_unused:UNUSED_PAD src0_sel:DWORD src1_sel:WORD_1
	v_cmp_lt_i32_e32 vcc, v157, v243
	v_lshl_add_u32 v247, v240, 8, v253
	global_load_dwordx4 v[220:223], v247, s[12:13]
	v_cndmask_b32_sdwa v240, v1, v250, vcc dst_sel:DWORD dst_unused:UNUSED_PAD src0_sel:DWORD src1_sel:WORD_0
	v_cmp_lt_i32_e32 vcc, v195, v243
	v_lshl_add_u32 v244, v240, 8, v253
	global_load_dwordx4 v[224:227], v244, s[12:13]
	v_cndmask_b32_sdwa v240, v1, v250, vcc dst_sel:DWORD dst_unused:UNUSED_PAD src0_sel:DWORD src1_sel:WORD_1
	v_cmp_lt_i32_e32 vcc, v196, v243
	v_lshl_add_u32 v245, v240, 8, v253
	global_load_dwordx4 v[228:231], v245, s[12:13]
	v_cndmask_b32_sdwa v240, v1, v251, vcc dst_sel:DWORD dst_unused:UNUSED_PAD src0_sel:DWORD src1_sel:WORD_0
	v_cmp_lt_i32_e32 vcc, v197, v243
	v_lshl_add_u32 v246, v240, 8, v253
	global_load_dwordx4 v[232:235], v246, s[12:13]
	v_cndmask_b32_sdwa v240, v1, v251, vcc dst_sel:DWORD dst_unused:UNUSED_PAD src0_sel:DWORD src1_sel:WORD_1
	v_lshl_add_u32 v247, v240, 8, v253
	global_load_dwordx4 v[236:239], v247, s[12:13]
	ds_read_b128 v[70:73], v68 offset:192
	s_waitcnt lgkmcnt(0)
	ds_read_b64_tr_b16 v[102:103], v162
	ds_read_b64_tr_b16 v[104:105], v163
	ds_read_b64_tr_b16 v[98:99], v164
	ds_read_b64_tr_b16 v[100:101], v165
	ds_read_b64_tr_b16 v[94:95], v166
	ds_read_b64_tr_b16 v[96:97], v167
	ds_read_b64_tr_b16 v[90:91], v168
	ds_read_b64_tr_b16 v[92:93], v169
	ds_read_b64_tr_b16 v[86:87], v170
	ds_read_b64_tr_b16 v[88:89], v171
	ds_read_b64_tr_b16 v[82:83], v172
	ds_read_b64_tr_b16 v[84:85], v173
	ds_read_b64_tr_b16 v[78:79], v174
	ds_read_b64_tr_b16 v[80:81], v175
	ds_read_b64_tr_b16 v[74:75], v176
	ds_read_b64_tr_b16 v[76:77], v177
	s_waitcnt lgkmcnt(0)
	v_mfma_f32_16x16x32_bf16 v[50:53], v[70:73], v[102:105], v[50:53]
	v_mfma_f32_16x16x32_bf16 v[38:41], v[70:73], v[98:101], v[38:41]
	v_mfma_f32_16x16x32_bf16 v[30:33], v[70:73], v[94:97], v[30:33]
	v_mfma_f32_16x16x32_bf16 v[18:21], v[70:73], v[90:93], v[18:21]
	v_mfma_f32_16x16x32_bf16 v[42:45], v[70:73], v[86:89], v[42:45]
	v_mfma_f32_16x16x32_bf16 v[26:29], v[70:73], v[82:85], v[26:29]
	v_mfma_f32_16x16x32_bf16 v[14:17], v[70:73], v[78:81], v[14:17]
	v_mfma_f32_16x16x32_bf16 v[6:9], v[70:73], v[74:77], v[6:9]
	s_waitcnt vmcnt(16)
	ds_write_b128 v198, v[106:109]
	ds_write_b128 v199, v[110:113]
	ds_write_b128 v200, v[114:117]
	ds_write_b128 v201, v[118:121]
	ds_write_b128 v202, v[122:125]
	ds_write_b128 v203, v[126:129]
	ds_write_b128 v204, v[130:133]
	ds_write_b128 v205, v[134:137]
	ds_read_b128 v[248:251], v242 offset:448
	s_waitcnt lgkmcnt(0)
	v_add_u32_e32 v243, 0xffffff20, v206
	v_cmp_lt_i32_e32 vcc, v156, v243
	s_nop 1
	v_cndmask_b32_sdwa v240, v1, v248, vcc dst_sel:DWORD dst_unused:UNUSED_PAD src0_sel:DWORD src1_sel:WORD_0
	v_cmp_lt_i32_e32 vcc, v192, v243
	v_lshl_add_u32 v244, v240, 8, v253
	global_load_dwordx4 v[106:109], v244, s[12:13]
	v_cndmask_b32_sdwa v240, v1, v248, vcc dst_sel:DWORD dst_unused:UNUSED_PAD src0_sel:DWORD src1_sel:WORD_1
	v_cmp_lt_i32_e32 vcc, v193, v243
	v_lshl_add_u32 v245, v240, 8, v253
	global_load_dwordx4 v[110:113], v245, s[12:13]
	v_cndmask_b32_sdwa v240, v1, v249, vcc dst_sel:DWORD dst_unused:UNUSED_PAD src0_sel:DWORD src1_sel:WORD_0
	v_cmp_lt_i32_e32 vcc, v194, v243
	v_lshl_add_u32 v246, v240, 8, v253
	global_load_dwordx4 v[114:117], v246, s[12:13]
	v_cndmask_b32_sdwa v240, v1, v249, vcc dst_sel:DWORD dst_unused:UNUSED_PAD src0_sel:DWORD src1_sel:WORD_1
	v_cmp_lt_i32_e32 vcc, v157, v243
	v_lshl_add_u32 v247, v240, 8, v253
	global_load_dwordx4 v[118:121], v247, s[12:13]
	v_cndmask_b32_sdwa v240, v1, v250, vcc dst_sel:DWORD dst_unused:UNUSED_PAD src0_sel:DWORD src1_sel:WORD_0
	v_cmp_lt_i32_e32 vcc, v195, v243
	v_lshl_add_u32 v244, v240, 8, v253
	global_load_dwordx4 v[122:125], v244, s[12:13]
	v_cndmask_b32_sdwa v240, v1, v250, vcc dst_sel:DWORD dst_unused:UNUSED_PAD src0_sel:DWORD src1_sel:WORD_1
	v_cmp_lt_i32_e32 vcc, v196, v243
	v_lshl_add_u32 v245, v240, 8, v253
	global_load_dwordx4 v[126:129], v245, s[12:13]
	v_cndmask_b32_sdwa v240, v1, v251, vcc dst_sel:DWORD dst_unused:UNUSED_PAD src0_sel:DWORD src1_sel:WORD_0
	v_cmp_lt_i32_e32 vcc, v197, v243
	v_lshl_add_u32 v246, v240, 8, v253
	global_load_dwordx4 v[130:133], v246, s[12:13]
	v_cndmask_b32_sdwa v240, v1, v251, vcc dst_sel:DWORD dst_unused:UNUSED_PAD src0_sel:DWORD src1_sel:WORD_1
	v_lshl_add_u32 v247, v240, 8, v253
	global_load_dwordx4 v[134:137], v247, s[12:13]
	ds_read_b128 v[70:73], v68 offset:256
	s_waitcnt lgkmcnt(0)
; #define MFMA16(a, b, c) __builtin_amdgcn_mfma_f32_16x16x32_bf16((a), (b), (c), 0, 0, 0)
; DI void dsa_item(const Params& p, int b, int blk) {
;     ...
;       const bf16x8 pa = *(const bf16x8*)(Pb + arow * PSTR + kc * 32 + g16 * 8);
;       u32x2 t0[8], t1[8];
;       asm volatile(
;           "s_waitcnt lgkmcnt(0)\n\t"
;           "ds_read_b64_tr_b16 %0, %16\n\tds_read_b64_tr_b16 %1, %17\n\tds_read_b64_tr_b16 %2, %18\n\tds_read_b64_tr_b16 %3, %19\n\t"
;           "ds_read_b64_tr_b16 %4, %20\n\tds_read_b64_tr_b16 %5, %21\n\tds_read_b64_tr_b16 %6, %22\n\tds_read_b64_tr_b16 %7, %23\n\t"
;           "ds_read_b64_tr_b16 %8, %24\n\tds_read_b64_tr_b16 %9, %25\n\tds_read_b64_tr_b16 %10, %26\n\tds_read_b64_tr_b16 %11, %27\n\t"
;           "ds_read_b64_tr_b16 %12, %28\n\tds_read_b64_tr_b16 %13, %29\n\tds_read_b64_tr_b16 %14, %30\n\tds_read_b64_tr_b16 %15, %31\n\t"
;           "s_waitcnt lgkmcnt(0)"
;           : "=&v"(t0[0]), "=&v"(t1[0]), "=&v"(t0[1]), "=&v"(t1[1]), "=&v"(t0[2]), "=&v"(t1[2]), "=&v"(t0[3]), "=&v"(t1[3]),
;             "=&v"(t0[4]), "=&v"(t1[4]), "=&v"(t0[5]), "=&v"(t1[5]), "=&v"(t0[6]), "=&v"(t1[6]), "=&v"(t0[7]), "=&v"(t1[7])
;           : "v"(lds_base + taddr[0][0]), "v"(lds_base + taddr[0][1]), "v"(lds_base + taddr[1][0]), "v"(lds_base + taddr[1][1]),
;             "v"(lds_base + taddr[2][0]), "v"(lds_base + taddr[2][1]), "v"(lds_base + taddr[3][0]), "v"(lds_base + taddr[3][1]),
;             "v"(lds_base + taddr[4][0]), "v"(lds_base + taddr[4][1]), "v"(lds_base + taddr[5][0]), "v"(lds_base + taddr[5][1]),
;             "v"(lds_base + taddr[6][0]), "v"(lds_base + taddr[6][1]), "v"(lds_base + taddr[7][0]), "v"(lds_base + taddr[7][1])
;           : "memory");
;       #pragma unroll
;       for (int c = 0; c < 8; ++c) {
;         u32x4 bv; bv[0] = t0[c][0]; bv[1] = t0[c][1]; bv[2] = t1[c][0]; bv[3] = t1[c][1];
;         oacc[c] = MFMA16(pa, __builtin_bit_cast(bf16x8, bv), oacc[c]);
;       }
;     }
	ds_read_b64_tr_b16 v[102:103], v162
	ds_read_b64_tr_b16 v[104:105], v163
	ds_read_b64_tr_b16 v[98:99], v164
	ds_read_b64_tr_b16 v[100:101], v165
	ds_read_b64_tr_b16 v[94:95], v166
	ds_read_b64_tr_b16 v[96:97], v167
	ds_read_b64_tr_b16 v[90:91], v168
	ds_read_b64_tr_b16 v[92:93], v169
	ds_read_b64_tr_b16 v[86:87], v170
	ds_read_b64_tr_b16 v[88:89], v171
	ds_read_b64_tr_b16 v[82:83], v172
	ds_read_b64_tr_b16 v[84:85], v173
	ds_read_b64_tr_b16 v[78:79], v174
	ds_read_b64_tr_b16 v[80:81], v175
	ds_read_b64_tr_b16 v[74:75], v176
	ds_read_b64_tr_b16 v[76:77], v177
	s_waitcnt lgkmcnt(0)
	v_mfma_f32_16x16x32_bf16 v[50:53], v[70:73], v[102:105], v[50:53]
	v_mfma_f32_16x16x32_bf16 v[38:41], v[70:73], v[98:101], v[38:41]
	v_mfma_f32_16x16x32_bf16 v[30:33], v[70:73], v[94:97], v[30:33]
	v_mfma_f32_16x16x32_bf16 v[18:21], v[70:73], v[90:93], v[18:21]
	v_mfma_f32_16x16x32_bf16 v[42:45], v[70:73], v[86:89], v[42:45]
	v_mfma_f32_16x16x32_bf16 v[26:29], v[70:73], v[82:85], v[26:29]
	v_mfma_f32_16x16x32_bf16 v[14:17], v[70:73], v[78:81], v[14:17]
	v_mfma_f32_16x16x32_bf16 v[6:9], v[70:73], v[74:77], v[6:9]
	s_waitcnt vmcnt(16)
	ds_write_b128 v198, v[2:5]
	ds_write_b128 v199, v[10:13]
	ds_write_b128 v200, v[22:25]
	ds_write_b128 v201, v[34:37]
	ds_write_b128 v202, v[46:49]
	ds_write_b128 v203, v[54:57]
	ds_write_b128 v204, v[58:61]
	ds_write_b128 v205, v[62:65]
	ds_read_b128 v[70:73], v68 offset:320
	s_waitcnt lgkmcnt(0)
	ds_read_b64_tr_b16 v[102:103], v162
	ds_read_b64_tr_b16 v[104:105], v163
	ds_read_b64_tr_b16 v[98:99], v164
	ds_read_b64_tr_b16 v[100:101], v165
	ds_read_b64_tr_b16 v[94:95], v166
	ds_read_b64_tr_b16 v[96:97], v167
	ds_read_b64_tr_b16 v[90:91], v168
	ds_read_b64_tr_b16 v[92:93], v169
	ds_read_b64_tr_b16 v[86:87], v170
	ds_read_b64_tr_b16 v[88:89], v171
	ds_read_b64_tr_b16 v[82:83], v172
	ds_read_b64_tr_b16 v[84:85], v173
	ds_read_b64_tr_b16 v[78:79], v174
	ds_read_b64_tr_b16 v[80:81], v175
	ds_read_b64_tr_b16 v[74:75], v176
	ds_read_b64_tr_b16 v[76:77], v177
	s_waitcnt lgkmcnt(0)
	v_mfma_f32_16x16x32_bf16 v[50:53], v[70:73], v[102:105], v[50:53]
	v_mfma_f32_16x16x32_bf16 v[38:41], v[70:73], v[98:101], v[38:41]
	v_mfma_f32_16x16x32_bf16 v[30:33], v[70:73], v[94:97], v[30:33]
	v_mfma_f32_16x16x32_bf16 v[18:21], v[70:73], v[90:93], v[18:21]
	v_mfma_f32_16x16x32_bf16 v[42:45], v[70:73], v[86:89], v[42:45]
	v_mfma_f32_16x16x32_bf16 v[26:29], v[70:73], v[82:85], v[26:29]
	v_mfma_f32_16x16x32_bf16 v[14:17], v[70:73], v[78:81], v[14:17]
	v_mfma_f32_16x16x32_bf16 v[6:9], v[70:73], v[74:77], v[6:9]
	s_waitcnt vmcnt(8)
	ds_write_b128 v198, v[208:211]
	ds_write_b128 v199, v[212:215]
	ds_write_b128 v200, v[216:219]
	ds_write_b128 v201, v[220:223]
	ds_write_b128 v202, v[224:227]
	ds_write_b128 v203, v[228:231]
	ds_write_b128 v204, v[232:235]
	ds_write_b128 v205, v[236:239]
	ds_read_b128 v[70:73], v68 offset:384
	s_waitcnt lgkmcnt(0)
	ds_read_b64_tr_b16 v[102:103], v162
	ds_read_b64_tr_b16 v[104:105], v163
	ds_read_b64_tr_b16 v[98:99], v164
	ds_read_b64_tr_b16 v[100:101], v165
	ds_read_b64_tr_b16 v[94:95], v166
	ds_read_b64_tr_b16 v[96:97], v167
	ds_read_b64_tr_b16 v[90:91], v168
	ds_read_b64_tr_b16 v[92:93], v169
	ds_read_b64_tr_b16 v[86:87], v170
	ds_read_b64_tr_b16 v[88:89], v171
	ds_read_b64_tr_b16 v[82:83], v172
	ds_read_b64_tr_b16 v[84:85], v173
	ds_read_b64_tr_b16 v[78:79], v174
	ds_read_b64_tr_b16 v[80:81], v175
	ds_read_b64_tr_b16 v[74:75], v176
	ds_read_b64_tr_b16 v[76:77], v177
	s_waitcnt lgkmcnt(0)
	v_mfma_f32_16x16x32_bf16 v[50:53], v[70:73], v[102:105], v[50:53]
	v_mfma_f32_16x16x32_bf16 v[38:41], v[70:73], v[98:101], v[38:41]
	v_mfma_f32_16x16x32_bf16 v[30:33], v[70:73], v[94:97], v[30:33]
	v_mfma_f32_16x16x32_bf16 v[18:21], v[70:73], v[90:93], v[18:21]
	v_mfma_f32_16x16x32_bf16 v[42:45], v[70:73], v[86:89], v[42:45]
	v_mfma_f32_16x16x32_bf16 v[26:29], v[70:73], v[82:85], v[26:29]
	v_mfma_f32_16x16x32_bf16 v[14:17], v[70:73], v[78:81], v[14:17]
	v_mfma_f32_16x16x32_bf16 v[6:9], v[70:73], v[74:77], v[6:9]
	s_waitcnt vmcnt(0)
	ds_write_b128 v198, v[106:109]
	ds_write_b128 v199, v[110:113]
	ds_write_b128 v200, v[114:117]
	ds_write_b128 v201, v[118:121]
	ds_write_b128 v202, v[122:125]
	ds_write_b128 v203, v[126:129]
	ds_write_b128 v204, v[130:133]
	ds_write_b128 v205, v[134:137]
	ds_read_b128 v[70:73], v68 offset:448
	s_waitcnt lgkmcnt(0)
	ds_read_b64_tr_b16 v[102:103], v162
	ds_read_b64_tr_b16 v[104:105], v163
	ds_read_b64_tr_b16 v[98:99], v164
	ds_read_b64_tr_b16 v[100:101], v165
	ds_read_b64_tr_b16 v[94:95], v166
	ds_read_b64_tr_b16 v[96:97], v167
	ds_read_b64_tr_b16 v[90:91], v168
	ds_read_b64_tr_b16 v[92:93], v169
	ds_read_b64_tr_b16 v[86:87], v170
	ds_read_b64_tr_b16 v[88:89], v171
	ds_read_b64_tr_b16 v[82:83], v172
	ds_read_b64_tr_b16 v[84:85], v173
	ds_read_b64_tr_b16 v[78:79], v174
	ds_read_b64_tr_b16 v[80:81], v175
	ds_read_b64_tr_b16 v[74:75], v176
	ds_read_b64_tr_b16 v[76:77], v177
	s_waitcnt lgkmcnt(0)
	v_mfma_f32_16x16x32_bf16 v[50:53], v[70:73], v[102:105], v[50:53]
	v_mfma_f32_16x16x32_bf16 v[38:41], v[70:73], v[98:101], v[38:41]
	v_mfma_f32_16x16x32_bf16 v[30:33], v[70:73], v[94:97], v[30:33]
	v_mfma_f32_16x16x32_bf16 v[18:21], v[70:73], v[90:93], v[18:21]
	v_mfma_f32_16x16x32_bf16 v[42:45], v[70:73], v[86:89], v[42:45]
	v_mfma_f32_16x16x32_bf16 v[26:29], v[70:73], v[82:85], v[26:29]
	v_mfma_f32_16x16x32_bf16 v[14:17], v[70:73], v[78:81], v[14:17]
	v_mfma_f32_16x16x32_bf16 v[6:9], v[70:73], v[74:77], v[6:9]
	s_nop 0
